# filter output epilogue vectorized over the 4 positions (packed bf16 stores), in1 rope epilogue LDS reads pipelined
# speedup vs baseline: 1.2007x; 1.0055x over previous
; DI bf16_t f2bf(float x) { return (bf16_t)(pack2(x, 0.f) & 0xffffu); }
; DI void hyena_filter_pos(const Params& p, int t, int w, int lane, float* sz, float* sh0, float* sh1) {
;   const float tn = (float)t / 4095.f;
;   const float wt = (6.283185307179586f * (float)t) / 4096.f;
;   if (lane < 33) {
;     float z;
;     if (lane == 0) z = tn;
;     else {
;       int i = (lane - 1) & 15;
;       float f = 1e-4f + (float)i * ((15.f - 1e-4f) / 15.f);
;       float fw = f * wt;
;       z = (lane <= 16) ? cosf(fw) : -sinf(fw);
;     }
;     sz[w * 40 + lane] = z;
;   }
;   __syncthreads();
;   const float fr = p.f_freq[lane];
;   float a = p.f_b1[lane];
; #pragma unroll 1
;   for (int i = 0; i < 33; ++i) a += sz[w * 40 + i] * p.f_w1[i * 64 + lane];
;   sh0[w * 64 + lane] = sinf(fr * a);
;   __syncthreads();
;   a = p.f_b2[lane];
; #pragma unroll 4
;   for (int i = 0; i < 64; ++i) a += sh0[w * 64 + i] * p.f_w2[i * 64 + lane];
;   sh1[w * 64 + lane] = sinf(fr * a);
;   __syncthreads();
;   a = p.f_b3[lane];
; #pragma unroll 4
;   for (int i = 0; i < 64; ++i) a += sh1[w * 64 + i] * p.f_w3[i * 64 + lane];
;   __syncthreads();
;   sh0[w * 64 + lane] = sinf(fr * a);
;   __syncthreads();
;   bf16_t* filt = (bf16_t*)(p.ws + OFF_FILT);
;   const float dmin = logf(1e-2f) / 1.5f, dmax = logf(1e-2f) / 0.3f;
; #pragma unroll 1
;   for (int i = 0; i < 16; ++i) {
;     int n = lane + 64 * i;
;     float o = 0.f;
; #pragma unroll 4
;     for (int k = 0; k < 64; ++k) o += sh0[w * 64 + k] * p.f_w4[k * 1024 + n];
;     int c = n & 511;
;     float delta = dmin + (float)c * ((dmax - dmin) / 511.f);
;     float win = expf(-tn * fabsf(delta));
;     o *= win;
;     if (n < 512) {
;       if (t == 0) o += p.hy_bias[c];
;       filt[(size_t)c * 8192 + 4096 + t] = f2bf(o);
;     } else {
;       if (t == 0) filt[(size_t)c * 8192] = 0;
;       else filt[(size_t)c * 8192 + 4096 - t] = f2bf(o);
;     }
;   }
;   __syncthreads();
; }
.LBB0_45:
	s_andn2_saveexec_b64 s[6:7], s[14:15]
	v_mul_f32_e64 v6, |v2|, s63
	v_rndne_f32_e32 v8, v6
	v_cvt_i32_f32_e32 v6, v8
	v_fma_f32 v7, v8, s64, |v2|
	v_fmac_f32_e32 v7, 0xb3a22168, v8
	v_fmac_f32_e32 v7, 0xa7c234c4, v8
	s_or_b64 exec, exec, s[6:7]
	v_mul_f32_e32 v8, v7, v7
	v_fmamk_f32 v9, v8, 0xb94c1982, v65
	v_fmaak_f32 v9, v8, v9, 0xbe2aaa9d
	v_mul_f32_e32 v9, v8, v9
	v_fmac_f32_e32 v7, v7, v9
	v_fmamk_f32 v9, v8, 0x37d75334, v66
	v_fmaak_f32 v9, v8, v9, 0x3d2aabf7
	v_fmaak_f32 v9, v8, v9, 0xbf000004
	v_fma_f32 v8, v8, v9, 1.0
	v_and_b32_e32 v9, 1, v6
	v_lshlrev_b32_e32 v6, 30, v6
	v_cmp_eq_u32_e32 vcc, 0, v9
	v_and_b32_e32 v6, 0x80000000, v6
	v_xor_b32_e32 v3, v3, v2
	v_cndmask_b32_e32 v7, v8, v7, vcc
	v_xor_b32_e32 v3, v3, v6
	v_xor_b32_e32 v3, v3, v7
	v_cmp_class_f32_e64 vcc, v2, s67
	s_mov_b32 s14, 0
	v_cmp_eq_u32_e64 s[6:7], 0, v4
	v_cndmask_b32_e32 v2, v71, v3, vcc
	ds_write_b32 v51, v2 offset:640
	v_cmp_ne_u32_e64 s[8:9], 0, v4
	v_mov_b64_e32 v[2:3], v[40:41]
	s_waitcnt lgkmcnt(0)
	s_barrier
	v_bfe_u32 v148, v196, 6, 2
	v_sub_u32_e32 v149, v4, v148
	v_add_u32_e32 v232, 0, v149
	v_cvt_f32_u32_e32 v2, v232
	v_div_scale_f32 v3, s[6:7], s53, s53, v2
	v_rcp_f32_e32 v5, v3
	v_div_scale_f32 v6, vcc, v2, s53, v2
	v_fma_f32 v7, -v3, v5, 1.0
	v_fmac_f32_e32 v5, v7, v5
	v_mul_f32_e32 v7, v6, v5
	v_fma_f32 v8, -v3, v7, v6
	v_fmac_f32_e32 v7, v8, v5
	v_fma_f32 v3, -v3, v7, v6
	v_div_fmas_f32 v3, v3, v5, v7
	v_div_fixup_f32 v236, v3, s53, v2
	v_add_u32_e32 v233, 1, v149
	v_cvt_f32_u32_e32 v2, v233
	v_div_scale_f32 v3, s[6:7], s53, s53, v2
	v_rcp_f32_e32 v5, v3
	v_div_scale_f32 v6, vcc, v2, s53, v2
	v_fma_f32 v7, -v3, v5, 1.0
	v_fmac_f32_e32 v5, v7, v5
	v_mul_f32_e32 v7, v6, v5
	v_fma_f32 v8, -v3, v7, v6
	v_fmac_f32_e32 v7, v8, v5
	v_fma_f32 v3, -v3, v7, v6
	v_div_fmas_f32 v3, v3, v5, v7
	v_div_fixup_f32 v237, v3, s53, v2
	v_add_u32_e32 v234, 2, v149
	v_cvt_f32_u32_e32 v2, v234
	v_div_scale_f32 v3, s[6:7], s53, s53, v2
	v_rcp_f32_e32 v5, v3
	v_div_scale_f32 v6, vcc, v2, s53, v2
	v_fma_f32 v7, -v3, v5, 1.0
	v_fmac_f32_e32 v5, v7, v5
	v_mul_f32_e32 v7, v6, v5
	v_fma_f32 v8, -v3, v7, v6
	v_fmac_f32_e32 v7, v8, v5
	v_fma_f32 v3, -v3, v7, v6
	v_div_fmas_f32 v3, v3, v5, v7
	v_div_fixup_f32 v238, v3, s53, v2
	v_add_u32_e32 v235, 3, v149
	v_cvt_f32_u32_e32 v2, v235
	v_div_scale_f32 v3, s[6:7], s53, s53, v2
	v_rcp_f32_e32 v5, v3
	v_div_scale_f32 v6, vcc, v2, s53, v2
	v_fma_f32 v7, -v3, v5, 1.0
	v_fmac_f32_e32 v5, v7, v5
	v_mul_f32_e32 v7, v6, v5
	v_fma_f32 v8, -v3, v7, v6
	v_fmac_f32_e32 v7, v8, v5
	v_fma_f32 v3, -v3, v7, v6
	v_div_fmas_f32 v3, v3, v5, v7
	v_div_fixup_f32 v239, v3, s53, v2
	v_readfirstlane_b32 s80, v148
	v_readlane_b32 s70, v40, 0
	v_readlane_b32 s71, v41, 0
	s_nop 1
	s_lshl_b32 s80, s80, 2
	s_add_u32 s72, s70, 0x10000
	s_addc_u32 s73, s71, 0
	s_add_u32 s74, s72, 0x10000
	s_addc_u32 s75, s73, 0
	s_add_u32 s76, s74, 0x10000
	s_addc_u32 s77, s75, 0
	v_subrev_u32_e32 v151, s70, v40
	v_lshl_add_u32 v151, v148, 10, v151
	v_add_u32_e32 v152, 0x1000, v151
	v_add_u32_e32 v153, 0x2000, v151
	v_add_u32_e32 v154, 0x3000, v151
	v_add_u32_e32 v155, 0x4000, v151
	v_add_u32_e32 v156, 0x5000, v151
	v_add_u32_e32 v157, 0x6000, v151
	v_add_u32_e32 v158, 0x7000, v151
	v_add_u32_e32 v159, 0x8000, v151
	v_add_u32_e32 v160, 0x9000, v151
	v_add_u32_e32 v161, 0xa000, v151
	v_add_u32_e32 v162, 0xb000, v151
	v_add_u32_e32 v163, 0xc000, v151
	v_add_u32_e32 v164, 0xd000, v151
	v_add_u32_e32 v165, 0xe000, v151
	v_add_u32_e32 v166, 0xf000, v151
	v_lshlrev_b32_e32 v149, 8, v148
	v_sub_u32_e32 v149, v54, v149
	v_and_b32_e32 v2, 3, v1
	v_lshl_add_u32 v149, v2, 8, v149
	ds_read_b128 v[80:83], v149
	ds_read_b128 v[84:87], v149 offset:16
	ds_read_b128 v[88:91], v149 offset:32
	ds_read_b128 v[92:95], v149 offset:48
	ds_read_b128 v[96:99], v149 offset:64
	ds_read_b128 v[100:103], v149 offset:80
	ds_read_b128 v[104:107], v149 offset:96
	ds_read_b128 v[108:111], v149 offset:112
	ds_read_b128 v[112:115], v149 offset:128
	ds_read_b128 v[116:119], v149 offset:144
	ds_read_b128 v[120:123], v149 offset:160
	ds_read_b128 v[124:127], v149 offset:176
	ds_read_b128 v[128:131], v149 offset:192
	ds_read_b128 v[132:135], v149 offset:208
	ds_read_b128 v[136:139], v149 offset:224
	ds_read_b128 v[140:143], v149 offset:240
	global_load_dword v167, v151, s[70:71]
	global_load_dword v168, v152, s[70:71]
	global_load_dword v169, v153, s[70:71]
	global_load_dword v170, v154, s[70:71]
	global_load_dword v171, v155, s[70:71]
	global_load_dword v172, v156, s[70:71]
	global_load_dword v173, v157, s[70:71]
	global_load_dword v174, v158, s[70:71]
	global_load_dword v175, v159, s[70:71]
	global_load_dword v176, v160, s[70:71]
	global_load_dword v177, v161, s[70:71]
	global_load_dword v178, v162, s[70:71]
	global_load_dword v179, v163, s[70:71]
	global_load_dword v180, v164, s[70:71]
	global_load_dword v181, v165, s[70:71]
	global_load_dword v182, v166, s[70:71]
	global_load_dword v183, v151, s[72:73]
	global_load_dword v184, v152, s[72:73]
	global_load_dword v185, v153, s[72:73]
	global_load_dword v186, v154, s[72:73]
	global_load_dword v187, v155, s[72:73]
	global_load_dword v188, v156, s[72:73]
	global_load_dword v189, v157, s[72:73]
	global_load_dword v190, v158, s[72:73]
	global_load_dword v191, v159, s[72:73]
	global_load_dword v192, v160, s[72:73]
	global_load_dword v193, v161, s[72:73]
	global_load_dword v194, v162, s[72:73]
	global_load_dword v195, v163, s[72:73]
	global_load_dword v197, v164, s[72:73]
	global_load_dword v198, v165, s[72:73]
	global_load_dword v199, v166, s[72:73]
	global_load_dword v200, v151, s[74:75]
	global_load_dword v201, v152, s[74:75]
	global_load_dword v202, v153, s[74:75]
	global_load_dword v203, v154, s[74:75]
	global_load_dword v204, v155, s[74:75]
	global_load_dword v205, v156, s[74:75]
	global_load_dword v206, v157, s[74:75]
	global_load_dword v207, v158, s[74:75]
	global_load_dword v208, v159, s[74:75]
	global_load_dword v209, v160, s[74:75]
	global_load_dword v210, v161, s[74:75]
	global_load_dword v211, v162, s[74:75]
	global_load_dword v212, v163, s[74:75]
	global_load_dword v213, v164, s[74:75]
	global_load_dword v214, v165, s[74:75]
	global_load_dword v215, v166, s[74:75]
	global_load_dword v216, v151, s[76:77]
	global_load_dword v217, v152, s[76:77]
	global_load_dword v218, v153, s[76:77]
	global_load_dword v219, v154, s[76:77]
	global_load_dword v220, v155, s[76:77]
	global_load_dword v221, v156, s[76:77]
	global_load_dword v222, v157, s[76:77]
	global_load_dword v223, v158, s[76:77]
	global_load_dword v224, v159, s[76:77]
	global_load_dword v225, v160, s[76:77]
	global_load_dword v226, v161, s[76:77]
	global_load_dword v227, v162, s[76:77]
	global_load_dword v228, v163, s[76:77]
	global_load_dword v229, v164, s[76:77]
	global_load_dword v230, v165, s[76:77]
	global_load_dword v231, v166, s[76:77]
	s_mov_b32 s78, 0
	v_readfirstlane_b32 s81, v232
	s_waitcnt lgkmcnt(0)
	s_branch .Lf_gi_loop

; DI bf16_t f2bf(float x) { return (bf16_t)(pack2(x, 0.f) & 0xffffu); }
; DI void hyena_filter_pos(const Params& p, int t, int w, int lane, float* sz, float* sh0, float* sh1) {
;     ...
;     int c = n & 511;
;     float delta = dmin + (float)c * ((dmax - dmin) / 511.f);
;     float win = expf(-tn * fabsf(delta));
;     o *= win;
;     if (n < 512) {
;       if (t == 0) o += p.hy_bias[c];
;       filt[(size_t)c * 8192 + 4096 + t] = f2bf(o);
;     } else {
;       if (t == 0) filt[(size_t)c * 8192] = 0;
;       else filt[(size_t)c * 8192 + 4096 - t] = f2bf(o);
;     }
;   }
.Lfilt_epi:
	s_nop 4
	s_add_u32 s14, s80, s78
	s_lshl_b32 s15, s14, 6
	v_bitop3_b32 v7, s15, v72, v1 bitop3:0xc8
	v_cvt_f32_u32_e32 v8, v7
	v_fmamk_f32 v12, v8, 0xbcc4df2d, v67
	v_mul_f32_e64 v8, |v12|, -v236
	s_mov_b32 s12, 0x3fb8aa3b
	v_mul_f32_e32 v9, 0x3fb8aa3b, v8
	v_fma_f32 v10, v8, s12, -v9
	v_rndne_f32_e32 v11, v9
	v_fmac_f32_e32 v10, 0x32a5705f, v8
	v_sub_f32_e32 v9, v9, v11
	v_add_f32_e32 v9, v9, v10
	v_cvt_i32_f32_e32 v11, v11
	v_exp_f32_e32 v9, v9
	s_mov_b32 s12, 0xc2ce8ed0
	v_cmp_ngt_f32_e32 vcc, s12, v8
	s_mov_b32 s12, 0x42b17218
	v_ldexp_f32 v9, v9, v11
	v_cndmask_b32_e32 v9, 0, v9, vcc
	v_cmp_nlt_f32_e32 vcc, s12, v8
	s_nop 1
	v_cndmask_b32_e32 v8, v73, v9, vcc
	v_mul_f32_e32 v144, v8, v144
	v_mul_f32_e64 v8, |v12|, -v237
	s_mov_b32 s12, 0x3fb8aa3b
	v_mul_f32_e32 v9, 0x3fb8aa3b, v8
	v_fma_f32 v10, v8, s12, -v9
	v_rndne_f32_e32 v11, v9
	v_fmac_f32_e32 v10, 0x32a5705f, v8
	v_sub_f32_e32 v9, v9, v11
	v_add_f32_e32 v9, v9, v10
	v_cvt_i32_f32_e32 v11, v11
	v_exp_f32_e32 v9, v9
	s_mov_b32 s12, 0xc2ce8ed0
	v_cmp_ngt_f32_e32 vcc, s12, v8
	s_mov_b32 s12, 0x42b17218
	v_ldexp_f32 v9, v9, v11
	v_cndmask_b32_e32 v9, 0, v9, vcc
	v_cmp_nlt_f32_e32 vcc, s12, v8
	s_nop 1
	v_cndmask_b32_e32 v8, v73, v9, vcc
	v_mul_f32_e32 v145, v8, v145
	v_mul_f32_e64 v8, |v12|, -v238
	s_mov_b32 s12, 0x3fb8aa3b
	v_mul_f32_e32 v9, 0x3fb8aa3b, v8
	v_fma_f32 v10, v8, s12, -v9
	v_rndne_f32_e32 v11, v9
	v_fmac_f32_e32 v10, 0x32a5705f, v8
	v_sub_f32_e32 v9, v9, v11
	v_add_f32_e32 v9, v9, v10
	v_cvt_i32_f32_e32 v11, v11
	v_exp_f32_e32 v9, v9
	s_mov_b32 s12, 0xc2ce8ed0
	v_cmp_ngt_f32_e32 vcc, s12, v8
	s_mov_b32 s12, 0x42b17218
	v_ldexp_f32 v9, v9, v11
	v_cndmask_b32_e32 v9, 0, v9, vcc
	v_cmp_nlt_f32_e32 vcc, s12, v8
	s_nop 1
	v_cndmask_b32_e32 v8, v73, v9, vcc
	v_mul_f32_e32 v146, v8, v146
	v_mul_f32_e64 v8, |v12|, -v239
	s_mov_b32 s12, 0x3fb8aa3b
	v_mul_f32_e32 v9, 0x3fb8aa3b, v8
	v_fma_f32 v10, v8, s12, -v9
	v_rndne_f32_e32 v11, v9
	v_fmac_f32_e32 v10, 0x32a5705f, v8
	v_sub_f32_e32 v9, v9, v11
	v_add_f32_e32 v9, v9, v10
	v_cvt_i32_f32_e32 v11, v11
	v_exp_f32_e32 v9, v9
	s_mov_b32 s12, 0xc2ce8ed0
	v_cmp_ngt_f32_e32 vcc, s12, v8
	s_mov_b32 s12, 0x42b17218
	v_ldexp_f32 v9, v9, v11
	v_cndmask_b32_e32 v9, 0, v9, vcc
	v_cmp_nlt_f32_e32 vcc, s12, v8
	s_nop 1
	v_cndmask_b32_e32 v8, v73, v9, vcc
	v_mul_f32_e32 v147, v8, v147
	s_cmp_gt_u32 s14, 7
	s_cbranch_scc1 .Lf_neg
	s_cmp_lg_u32 s81, 0
	s_cbranch_scc1 .Lf_pos_store
	v_lshlrev_b32_e32 v9, 2, v7
	global_load_dword v9, v9, s[84:85]
	s_waitcnt vmcnt(0)
	v_add_f32_e32 v144, v144, v9
.Lf_pos_store:
	v_cvt_pk_bf16_f32 v10, v144, v145
	v_cvt_pk_bf16_f32 v11, v146, v147
	v_lshl_add_u32 v18, v7, 13, v232
	v_add_u32_e32 v18, 0x1000, v18
	v_lshl_add_u64 v[8:9], v[18:19], 1, s[18:19]
	global_store_dwordx2 v[8:9], v[10:11], off
	s_branch .Lf_latch
.Lf_neg:
	v_lshlrev_b32_e32 v18, 13, v7
	v_add_u32_e32 v18, 0x1000, v18
	v_sub_u32_e32 v18, v18, v232
	v_lshl_add_u64 v[8:9], v[18:19], 1, s[18:19]
	v_cvt_pk_bf16_f32 v10, v147, v147
	v_cvt_pk_bf16_f32 v11, v146, v145
	global_store_short v[8:9], v10, off offset:-6
	global_store_dword v[8:9], v11, off offset:-4
	s_cmp_lg_u32 s81, 0
	s_cbranch_scc1 .Lf_neg_p0
	v_lshlrev_b32_e32 v8, 14, v7
	global_store_short v8, v19, s[18:19]
	s_branch .Lf_latch
.Lf_neg_p0:
	v_cvt_pk_bf16_f32 v10, v144, v144
	s_nop 0
	global_store_short v[8:9], v10, off
.Lf_latch:
	s_add_u32 s78, s78, 1
	s_cmp_lt_u32 s78, 4
	s_cbranch_scc1 .Lf_gi_loop
	s_branch .LBB0_62

; #define G_LOADA(kt_) { _Pragma("unroll") for (int i = 0; i < 4; ++i) ra[i] = al(lrow + 64 * i, (kt_) * 64 + lck * 8); }
; #define G_LOADB(kt_) { _Pragma("unroll") for (int i = 0; i < 4; ++i) rb[i] = bl(lrow + 64 * i, (kt_) * 64 + lck * 8); }
; #define G_STOREA(buf_) { bf16_t* nA = sA + (buf_) * 256 * GLD; _Pragma("unroll") for (int i = 0; i < 4; ++i) *(u32x4*)(nA + (lrow + 64 * i) * GLD + lck * 8) = ra[i]; }
; #define G_STOREB(buf_) { bf16_t* nB = sB + (buf_) * 256 * GLD; _Pragma("unroll") for (int i = 0; i < 4; ++i) *(u32x4*)(nB + (lrow + 64 * i) * GLD + lck * 8) = rb[i]; }
; template <class AL, class BL, class EP>
; DI void gemm_tile256(AL al, BL bl, EP ep, int K, char* smem) {
;     ...
;   G_LOADA(0); G_LOADB(0);
;   __syncthreads();
;   G_STOREA(0); G_STOREB(0);
;   if (KT > 1) G_LOADB(1);
;   __syncthreads();
;   for (int kt = 0; kt < KT; kt += 2) {
;     G_STEP(0, kt);
;     if (kt + 1 >= KT) break;
;     G_STEP(1, kt + 1);
;   }
.Lgk_ph9_loop:
	s_waitcnt lgkmcnt(0)
	v_mfma_f32_32x32x16_bf16 v[112:127], v[188:191], v[156:159], v[112:127]
	ds_read_b128 v[200:203], v155
	ds_read_b128 v[172:175], v153
	v_mfma_f32_32x32x16_bf16 v[96:111], v[192:195], v[156:159], v[96:111]
	ds_read_b128 v[204:207], v155 offset:2048
	ds_read_b128 v[176:179], v153 offset:2048
	v_mfma_f32_32x32x16_bf16 v[80:95], v[188:191], v[160:163], v[80:95]
	ds_read_b128 v[180:183], v153 offset:4096
	ds_read_b128 v[184:187], v153 offset:6144
	v_mfma_f32_32x32x16_bf16 v[64:79], v[192:195], v[160:163], v[64:79]
	s_add_u32 m0, s21, 0x22000
	s_nop 0
	global_load_lds_dwordx4 v[216:217], off
	v_lshl_add_u64 v[216:217], v[216:217], 0, s[6:7]
	v_mfma_f32_32x32x16_bf16 v[48:63], v[188:191], v[164:167], v[48:63]
	v_mfma_f32_32x32x16_bf16 v[32:47], v[192:195], v[164:167], v[32:47]
	v_mfma_f32_32x32x16_bf16 v[16:31], v[188:191], v[168:171], v[16:31]
	v_mfma_f32_32x32x16_bf16 v[0:15], v[192:195], v[168:171], v[0:15]
	s_add_u32 m0, s21, 0x26000
	s_nop 0
	global_load_lds_dwordx4 v[220:221], off
	v_lshl_add_u64 v[220:221], v[220:221], 0, s[6:7]
	s_waitcnt lgkmcnt(0)
	s_waitcnt vmcnt(12)
	s_barrier
	s_waitcnt lgkmcnt(0)
	v_mfma_f32_32x32x16_bf16 v[112:127], v[200:203], v[172:175], v[112:127]
	ds_read_b128 v[188:191], v154 offset:32768
	ds_read_b128 v[156:159], v132 offset:32768
	v_mfma_f32_32x32x16_bf16 v[96:111], v[204:207], v[172:175], v[96:111]
	ds_read_b128 v[192:195], v154 offset:34816
	ds_read_b128 v[160:163], v132 offset:34816
	v_mfma_f32_32x32x16_bf16 v[80:95], v[200:203], v[176:179], v[80:95]
	ds_read_b128 v[164:167], v132 offset:36864
	ds_read_b128 v[168:171], v132 offset:38912
	v_mfma_f32_32x32x16_bf16 v[64:79], v[204:207], v[176:179], v[64:79]
	s_add_u32 m0, s21, 0x0
	s_nop 0
	global_load_lds_dwordx4 v[214:215], off
	v_lshl_add_u64 v[214:215], v[214:215], 0, s[6:7]
	v_mfma_f32_32x32x16_bf16 v[48:63], v[200:203], v[180:183], v[48:63]
	v_mfma_f32_32x32x16_bf16 v[32:47], v[204:207], v[180:183], v[32:47]
	v_mfma_f32_32x32x16_bf16 v[16:31], v[200:203], v[184:187], v[16:31]
	v_mfma_f32_32x32x16_bf16 v[0:15], v[204:207], v[184:187], v[0:15]
	s_add_u32 m0, s21, 0x4000
	s_nop 0
	global_load_lds_dwordx4 v[218:219], off
	v_lshl_add_u64 v[218:219], v[218:219], 0, s[6:7]
	s_waitcnt lgkmcnt(0)
	v_mfma_f32_32x32x16_bf16 v[112:127], v[188:191], v[156:159], v[112:127]
	ds_read_b128 v[200:203], v155 offset:32768
	ds_read_b128 v[172:175], v153 offset:32768
	v_mfma_f32_32x32x16_bf16 v[96:111], v[192:195], v[156:159], v[96:111]
	ds_read_b128 v[204:207], v155 offset:34816
	ds_read_b128 v[176:179], v153 offset:34816
	v_mfma_f32_32x32x16_bf16 v[80:95], v[188:191], v[160:163], v[80:95]
	ds_read_b128 v[180:183], v153 offset:36864
	ds_read_b128 v[184:187], v153 offset:38912
	v_mfma_f32_32x32x16_bf16 v[64:79], v[192:195], v[160:163], v[64:79]
	s_add_u32 m0, s21, 0x2000
	s_nop 0
	global_load_lds_dwordx4 v[216:217], off
	v_lshl_add_u64 v[216:217], v[216:217], 0, s[6:7]
	v_mfma_f32_32x32x16_bf16 v[48:63], v[188:191], v[164:167], v[48:63]
	v_mfma_f32_32x32x16_bf16 v[32:47], v[192:195], v[164:167], v[32:47]
	v_mfma_f32_32x32x16_bf16 v[16:31], v[188:191], v[168:171], v[16:31]
	v_mfma_f32_32x32x16_bf16 v[0:15], v[192:195], v[168:171], v[0:15]
	s_add_u32 m0, s21, 0x6000
	s_nop 0
	global_load_lds_dwordx4 v[220:221], off
	v_lshl_add_u64 v[220:221], v[220:221], 0, s[6:7]
	s_waitcnt lgkmcnt(0)
	s_waitcnt vmcnt(12)
	s_barrier
	s_waitcnt lgkmcnt(0)
	v_mfma_f32_32x32x16_bf16 v[112:127], v[200:203], v[172:175], v[112:127]
	ds_read_b128 v[188:191], v208
	ds_read_b128 v[156:159], v198
	v_mfma_f32_32x32x16_bf16 v[96:111], v[204:207], v[172:175], v[96:111]
	ds_read_b128 v[192:195], v208 offset:2048
	ds_read_b128 v[160:163], v198 offset:2048
	v_mfma_f32_32x32x16_bf16 v[80:95], v[200:203], v[176:179], v[80:95]
	ds_read_b128 v[164:167], v198 offset:4096
	ds_read_b128 v[168:171], v198 offset:6144
	v_mfma_f32_32x32x16_bf16 v[64:79], v[204:207], v[176:179], v[64:79]
	s_add_u32 m0, s21, 0x8000
	s_nop 0
	global_load_lds_dwordx4 v[214:215], off
	v_lshl_add_u64 v[214:215], v[214:215], 0, s[6:7]
	v_mfma_f32_32x32x16_bf16 v[48:63], v[200:203], v[180:183], v[48:63]
	v_mfma_f32_32x32x16_bf16 v[32:47], v[204:207], v[180:183], v[32:47]
	v_mfma_f32_32x32x16_bf16 v[16:31], v[200:203], v[184:187], v[16:31]
	v_mfma_f32_32x32x16_bf16 v[0:15], v[204:207], v[184:187], v[0:15]
	s_add_u32 m0, s21, 0xc000
	s_nop 0
	global_load_lds_dwordx4 v[218:219], off
	v_lshl_add_u64 v[218:219], v[218:219], 0, s[6:7]
	s_waitcnt lgkmcnt(0)
	v_mfma_f32_32x32x16_bf16 v[112:127], v[188:191], v[156:159], v[112:127]
	ds_read_b128 v[200:203], v209
	ds_read_b128 v[172:175], v199
	v_mfma_f32_32x32x16_bf16 v[96:111], v[192:195], v[156:159], v[96:111]
	ds_read_b128 v[204:207], v209 offset:2048
	ds_read_b128 v[176:179], v199 offset:2048
	v_mfma_f32_32x32x16_bf16 v[80:95], v[188:191], v[160:163], v[80:95]
	ds_read_b128 v[180:183], v199 offset:4096
	ds_read_b128 v[184:187], v199 offset:6144
	v_mfma_f32_32x32x16_bf16 v[64:79], v[192:195], v[160:163], v[64:79]
	s_add_u32 m0, s21, 0xa000
	s_nop 0
	global_load_lds_dwordx4 v[216:217], off
	v_lshl_add_u64 v[216:217], v[216:217], 0, s[6:7]
	v_mfma_f32_32x32x16_bf16 v[48:63], v[188:191], v[164:167], v[48:63]
	v_mfma_f32_32x32x16_bf16 v[32:47], v[192:195], v[164:167], v[32:47]
	v_mfma_f32_32x32x16_bf16 v[16:31], v[188:191], v[168:171], v[16:31]
	v_mfma_f32_32x32x16_bf16 v[0:15], v[192:195], v[168:171], v[0:15]
	s_add_u32 m0, s21, 0xe000
	s_nop 0
	global_load_lds_dwordx4 v[220:221], off
	v_lshl_add_u64 v[220:221], v[220:221], 0, s[6:7]
	s_waitcnt lgkmcnt(0)
	s_waitcnt vmcnt(12)
	s_barrier
; #define G_LOADA(kt_) { _Pragma("unroll") for (int i = 0; i < 4; ++i) ra[i] = al(lrow + 64 * i, (kt_) * 64 + lck * 8); }
; #define G_LOADB(kt_) { _Pragma("unroll") for (int i = 0; i < 4; ++i) rb[i] = bl(lrow + 64 * i, (kt_) * 64 + lck * 8); }
; #define G_STOREA(buf_) { bf16_t* nA = sA + (buf_) * 256 * GLD; _Pragma("unroll") for (int i = 0; i < 4; ++i) *(u32x4*)(nA + (lrow + 64 * i) * GLD + lck * 8) = ra[i]; }
; #define G_STOREB(buf_) { bf16_t* nB = sB + (buf_) * 256 * GLD; _Pragma("unroll") for (int i = 0; i < 4; ++i) *(u32x4*)(nB + (lrow + 64 * i) * GLD + lck * 8) = rb[i]; }
; template <class AL, class BL, class EP>
; DI void gemm_tile256(AL al, BL bl, EP ep, int K, char* smem) {
;     ...
;   G_LOADA(0); G_LOADB(0);
;   __syncthreads();
;   G_STOREA(0); G_STOREB(0);
;   if (KT > 1) G_LOADB(1);
;   __syncthreads();
;   for (int kt = 0; kt < KT; kt += 2) {
;     G_STEP(0, kt);
;     if (kt + 1 >= KT) break;
;     G_STEP(1, kt + 1);
;   }
	s_waitcnt lgkmcnt(0)
	v_mfma_f32_32x32x16_bf16 v[112:127], v[200:203], v[172:175], v[112:127]
	ds_read_b128 v[188:191], v208 offset:32768
	ds_read_b128 v[156:159], v198 offset:32768
	v_mfma_f32_32x32x16_bf16 v[96:111], v[204:207], v[172:175], v[96:111]
	ds_read_b128 v[192:195], v208 offset:34816
	ds_read_b128 v[160:163], v198 offset:34816
	v_mfma_f32_32x32x16_bf16 v[80:95], v[200:203], v[176:179], v[80:95]
	ds_read_b128 v[164:167], v198 offset:36864
	ds_read_b128 v[168:171], v198 offset:38912
	v_mfma_f32_32x32x16_bf16 v[64:79], v[204:207], v[176:179], v[64:79]
	s_add_u32 m0, s21, 0x10000
	s_nop 0
	global_load_lds_dwordx4 v[214:215], off
	v_lshl_add_u64 v[214:215], v[214:215], 0, s[6:7]
	v_mfma_f32_32x32x16_bf16 v[48:63], v[200:203], v[180:183], v[48:63]
	v_mfma_f32_32x32x16_bf16 v[32:47], v[204:207], v[180:183], v[32:47]
	v_mfma_f32_32x32x16_bf16 v[16:31], v[200:203], v[184:187], v[16:31]
	v_mfma_f32_32x32x16_bf16 v[0:15], v[204:207], v[184:187], v[0:15]
	s_add_u32 m0, s21, 0x14000
	s_nop 0
	global_load_lds_dwordx4 v[218:219], off
	v_lshl_add_u64 v[218:219], v[218:219], 0, s[6:7]
	s_waitcnt lgkmcnt(0)
	v_mfma_f32_32x32x16_bf16 v[112:127], v[188:191], v[156:159], v[112:127]
	ds_read_b128 v[200:203], v209 offset:32768
	ds_read_b128 v[172:175], v199 offset:32768
	v_mfma_f32_32x32x16_bf16 v[96:111], v[192:195], v[156:159], v[96:111]
	ds_read_b128 v[204:207], v209 offset:34816
	ds_read_b128 v[176:179], v199 offset:34816
	v_mfma_f32_32x32x16_bf16 v[80:95], v[188:191], v[160:163], v[80:95]
	ds_read_b128 v[180:183], v199 offset:36864
	ds_read_b128 v[184:187], v199 offset:38912
	v_mfma_f32_32x32x16_bf16 v[64:79], v[192:195], v[160:163], v[64:79]
	s_add_u32 m0, s21, 0x12000
	s_nop 0
	global_load_lds_dwordx4 v[216:217], off
	v_lshl_add_u64 v[216:217], v[216:217], 0, s[6:7]
	v_mfma_f32_32x32x16_bf16 v[48:63], v[188:191], v[164:167], v[48:63]
	v_mfma_f32_32x32x16_bf16 v[32:47], v[192:195], v[164:167], v[32:47]
	v_mfma_f32_32x32x16_bf16 v[16:31], v[188:191], v[168:171], v[16:31]
	v_mfma_f32_32x32x16_bf16 v[0:15], v[192:195], v[168:171], v[0:15]
	s_add_u32 m0, s21, 0x16000
	s_nop 0
	global_load_lds_dwordx4 v[220:221], off
	v_lshl_add_u64 v[220:221], v[220:221], 0, s[6:7]
	s_waitcnt lgkmcnt(0)
	s_waitcnt vmcnt(12)
	s_barrier
	s_waitcnt lgkmcnt(0)
	v_mfma_f32_32x32x16_bf16 v[112:127], v[200:203], v[172:175], v[112:127]
	ds_read_b128 v[188:191], v212
	ds_read_b128 v[156:159], v210
	v_mfma_f32_32x32x16_bf16 v[96:111], v[204:207], v[172:175], v[96:111]
	ds_read_b128 v[192:195], v212 offset:2048
	ds_read_b128 v[160:163], v210 offset:2048
	v_mfma_f32_32x32x16_bf16 v[80:95], v[200:203], v[176:179], v[80:95]
	ds_read_b128 v[164:167], v210 offset:4096
	ds_read_b128 v[168:171], v210 offset:6144
	v_mfma_f32_32x32x16_bf16 v[64:79], v[204:207], v[176:179], v[64:79]
	s_add_u32 m0, s21, 0x18000
	s_nop 0
	global_load_lds_dwordx4 v[214:215], off
	v_lshl_add_u64 v[214:215], v[214:215], 0, s[6:7]
	v_mfma_f32_32x32x16_bf16 v[48:63], v[200:203], v[180:183], v[48:63]
	v_mfma_f32_32x32x16_bf16 v[32:47], v[204:207], v[180:183], v[32:47]
	v_mfma_f32_32x32x16_bf16 v[16:31], v[200:203], v[184:187], v[16:31]
	v_mfma_f32_32x32x16_bf16 v[0:15], v[204:207], v[184:187], v[0:15]
	s_add_u32 m0, s21, 0x1c000
	s_nop 0
	global_load_lds_dwordx4 v[218:219], off
	v_lshl_add_u64 v[218:219], v[218:219], 0, s[6:7]
	s_waitcnt lgkmcnt(0)
	v_mfma_f32_32x32x16_bf16 v[112:127], v[188:191], v[156:159], v[112:127]
	ds_read_b128 v[200:203], v213
	ds_read_b128 v[172:175], v211
	v_mfma_f32_32x32x16_bf16 v[96:111], v[192:195], v[156:159], v[96:111]
	ds_read_b128 v[204:207], v213 offset:2048
	ds_read_b128 v[176:179], v211 offset:2048
	v_mfma_f32_32x32x16_bf16 v[80:95], v[188:191], v[160:163], v[80:95]
	ds_read_b128 v[180:183], v211 offset:4096
	ds_read_b128 v[184:187], v211 offset:6144
	v_mfma_f32_32x32x16_bf16 v[64:79], v[192:195], v[160:163], v[64:79]
	s_add_u32 m0, s21, 0x1a000
	s_nop 0
	global_load_lds_dwordx4 v[216:217], off
	v_lshl_add_u64 v[216:217], v[216:217], 0, s[6:7]
	v_mfma_f32_32x32x16_bf16 v[48:63], v[188:191], v[164:167], v[48:63]
	v_mfma_f32_32x32x16_bf16 v[32:47], v[192:195], v[164:167], v[32:47]
	v_mfma_f32_32x32x16_bf16 v[16:31], v[188:191], v[168:171], v[16:31]
	v_mfma_f32_32x32x16_bf16 v[0:15], v[192:195], v[168:171], v[0:15]
	s_add_u32 m0, s21, 0x1e000
	s_nop 0
	global_load_lds_dwordx4 v[220:221], off
	v_lshl_add_u64 v[220:221], v[220:221], 0, s[6:7]
	s_waitcnt lgkmcnt(0)
	s_waitcnt vmcnt(12)
	s_barrier
	s_waitcnt lgkmcnt(0)
	v_mfma_f32_32x32x16_bf16 v[112:127], v[200:203], v[172:175], v[112:127]
	ds_read_b128 v[188:191], v154
	ds_read_b128 v[156:159], v132
	v_mfma_f32_32x32x16_bf16 v[96:111], v[204:207], v[172:175], v[96:111]
	ds_read_b128 v[192:195], v154 offset:2048
	ds_read_b128 v[160:163], v132 offset:2048
	v_mfma_f32_32x32x16_bf16 v[80:95], v[200:203], v[176:179], v[80:95]
	ds_read_b128 v[164:167], v132 offset:4096
	ds_read_b128 v[168:171], v132 offset:6144
	v_mfma_f32_32x32x16_bf16 v[64:79], v[204:207], v[176:179], v[64:79]
	s_add_u32 m0, s21, 0x20000
	s_nop 0
	global_load_lds_dwordx4 v[214:215], off
	v_lshl_add_u64 v[214:215], v[214:215], 0, s[6:7]
	v_mfma_f32_32x32x16_bf16 v[48:63], v[200:203], v[180:183], v[48:63]
	v_mfma_f32_32x32x16_bf16 v[32:47], v[204:207], v[180:183], v[32:47]
	v_mfma_f32_32x32x16_bf16 v[16:31], v[200:203], v[184:187], v[16:31]
	v_mfma_f32_32x32x16_bf16 v[0:15], v[204:207], v[184:187], v[0:15]
	s_add_u32 m0, s21, 0x24000
	s_nop 0
	global_load_lds_dwordx4 v[218:219], off
	v_lshl_add_u64 v[218:219], v[218:219], 0, s[6:7]
	s_sub_u32 s25, s25, 1
	s_cmp_lg_u32 s25, 0
	s_cbranch_scc1 .Lgk_ph9_loop
; #define G_LOADA(kt_) { _Pragma("unroll") for (int i = 0; i < 4; ++i) ra[i] = al(lrow + 64 * i, (kt_) * 64 + lck * 8); }
; #define G_LOADB(kt_) { _Pragma("unroll") for (int i = 0; i < 4; ++i) rb[i] = bl(lrow + 64 * i, (kt_) * 64 + lck * 8); }
; #define G_STOREA(buf_) { bf16_t* nA = sA + (buf_) * 256 * GLD; _Pragma("unroll") for (int i = 0; i < 4; ++i) *(u32x4*)(nA + (lrow + 64 * i) * GLD + lck * 8) = ra[i]; }
; #define G_STOREB(buf_) { bf16_t* nB = sB + (buf_) * 256 * GLD; _Pragma("unroll") for (int i = 0; i < 4; ++i) *(u32x4*)(nB + (lrow + 64 * i) * GLD + lck * 8) = rb[i]; }
; template <class AL, class BL, class EP>
; DI void gemm_tile256(AL al, BL bl, EP ep, int K, char* smem) {
;     ...
;   G_LOADA(0); G_LOADB(0);
;   __syncthreads();
;   G_STOREA(0); G_STOREB(0);
;   if (KT > 1) G_LOADB(1);
;   __syncthreads();
;   for (int kt = 0; kt < KT; kt += 2) {
;     G_STEP(0, kt);
;     if (kt + 1 >= KT) break;
;     G_STEP(1, kt + 1);
;   }
	s_waitcnt lgkmcnt(0)
	v_mfma_f32_32x32x16_bf16 v[112:127], v[188:191], v[156:159], v[112:127]
	ds_read_b128 v[200:203], v155
	ds_read_b128 v[172:175], v153
	v_mfma_f32_32x32x16_bf16 v[96:111], v[192:195], v[156:159], v[96:111]
	ds_read_b128 v[204:207], v155 offset:2048
	ds_read_b128 v[176:179], v153 offset:2048
	v_mfma_f32_32x32x16_bf16 v[80:95], v[188:191], v[160:163], v[80:95]
	ds_read_b128 v[180:183], v153 offset:4096
	ds_read_b128 v[184:187], v153 offset:6144
	v_mfma_f32_32x32x16_bf16 v[64:79], v[192:195], v[160:163], v[64:79]
	s_add_u32 m0, s21, 0x22000
	s_nop 0
	global_load_lds_dwordx4 v[216:217], off
	v_lshl_add_u64 v[216:217], v[216:217], 0, s[6:7]
	v_mfma_f32_32x32x16_bf16 v[48:63], v[188:191], v[164:167], v[48:63]
	v_mfma_f32_32x32x16_bf16 v[32:47], v[192:195], v[164:167], v[32:47]
	v_mfma_f32_32x32x16_bf16 v[16:31], v[188:191], v[168:171], v[16:31]
	v_mfma_f32_32x32x16_bf16 v[0:15], v[192:195], v[168:171], v[0:15]
	s_add_u32 m0, s21, 0x26000
	s_nop 0
	global_load_lds_dwordx4 v[220:221], off
	v_lshl_add_u64 v[220:221], v[220:221], 0, s[6:7]
	s_waitcnt lgkmcnt(0)
	s_waitcnt vmcnt(12)
	s_barrier
	s_waitcnt lgkmcnt(0)
	v_mfma_f32_32x32x16_bf16 v[112:127], v[200:203], v[172:175], v[112:127]
	ds_read_b128 v[188:191], v154 offset:32768
	ds_read_b128 v[156:159], v132 offset:32768
	v_mfma_f32_32x32x16_bf16 v[96:111], v[204:207], v[172:175], v[96:111]
	ds_read_b128 v[192:195], v154 offset:34816
	ds_read_b128 v[160:163], v132 offset:34816
	v_mfma_f32_32x32x16_bf16 v[80:95], v[200:203], v[176:179], v[80:95]
	ds_read_b128 v[164:167], v132 offset:36864
	ds_read_b128 v[168:171], v132 offset:38912
	v_mfma_f32_32x32x16_bf16 v[64:79], v[204:207], v[176:179], v[64:79]
	s_add_u32 m0, s21, 0x0
	s_nop 0
	global_load_lds_dwordx4 v[214:215], off
	v_lshl_add_u64 v[214:215], v[214:215], 0, s[6:7]
	v_mfma_f32_32x32x16_bf16 v[48:63], v[200:203], v[180:183], v[48:63]
	v_mfma_f32_32x32x16_bf16 v[32:47], v[204:207], v[180:183], v[32:47]
	v_mfma_f32_32x32x16_bf16 v[16:31], v[200:203], v[184:187], v[16:31]
	v_mfma_f32_32x32x16_bf16 v[0:15], v[204:207], v[184:187], v[0:15]
	s_add_u32 m0, s21, 0x4000
	s_nop 0
	global_load_lds_dwordx4 v[218:219], off
	v_lshl_add_u64 v[218:219], v[218:219], 0, s[6:7]
	s_waitcnt lgkmcnt(0)
	v_mfma_f32_32x32x16_bf16 v[112:127], v[188:191], v[156:159], v[112:127]
	ds_read_b128 v[200:203], v155 offset:32768
	ds_read_b128 v[172:175], v153 offset:32768
	v_mfma_f32_32x32x16_bf16 v[96:111], v[192:195], v[156:159], v[96:111]
	ds_read_b128 v[204:207], v155 offset:34816
	ds_read_b128 v[176:179], v153 offset:34816
	v_mfma_f32_32x32x16_bf16 v[80:95], v[188:191], v[160:163], v[80:95]
	ds_read_b128 v[180:183], v153 offset:36864
	ds_read_b128 v[184:187], v153 offset:38912
	v_mfma_f32_32x32x16_bf16 v[64:79], v[192:195], v[160:163], v[64:79]
	s_add_u32 m0, s21, 0x2000
	s_nop 0
	global_load_lds_dwordx4 v[216:217], off
	v_lshl_add_u64 v[216:217], v[216:217], 0, s[6:7]
	v_mfma_f32_32x32x16_bf16 v[48:63], v[188:191], v[164:167], v[48:63]
	v_mfma_f32_32x32x16_bf16 v[32:47], v[192:195], v[164:167], v[32:47]
	v_mfma_f32_32x32x16_bf16 v[16:31], v[188:191], v[168:171], v[16:31]
	v_mfma_f32_32x32x16_bf16 v[0:15], v[192:195], v[168:171], v[0:15]
	s_add_u32 m0, s21, 0x6000
	s_nop 0
	global_load_lds_dwordx4 v[220:221], off
	v_lshl_add_u64 v[220:221], v[220:221], 0, s[6:7]
	s_waitcnt lgkmcnt(0)
	s_waitcnt vmcnt(12)
	s_barrier
	s_waitcnt lgkmcnt(0)
	v_mfma_f32_32x32x16_bf16 v[112:127], v[200:203], v[172:175], v[112:127]
	ds_read_b128 v[188:191], v208
	ds_read_b128 v[156:159], v198
	v_mfma_f32_32x32x16_bf16 v[96:111], v[204:207], v[172:175], v[96:111]
	ds_read_b128 v[192:195], v208 offset:2048
	ds_read_b128 v[160:163], v198 offset:2048
	v_mfma_f32_32x32x16_bf16 v[80:95], v[200:203], v[176:179], v[80:95]
	ds_read_b128 v[164:167], v198 offset:4096
	ds_read_b128 v[168:171], v198 offset:6144
	v_mfma_f32_32x32x16_bf16 v[64:79], v[204:207], v[176:179], v[64:79]
	s_add_u32 m0, s21, 0x8000
	s_nop 0
	global_load_lds_dwordx4 v[214:215], off
	v_lshl_add_u64 v[214:215], v[214:215], 0, s[6:7]
	v_mfma_f32_32x32x16_bf16 v[48:63], v[200:203], v[180:183], v[48:63]
	v_mfma_f32_32x32x16_bf16 v[32:47], v[204:207], v[180:183], v[32:47]
	v_mfma_f32_32x32x16_bf16 v[16:31], v[200:203], v[184:187], v[16:31]
	v_mfma_f32_32x32x16_bf16 v[0:15], v[204:207], v[184:187], v[0:15]
	s_add_u32 m0, s21, 0xc000
	s_nop 0
	global_load_lds_dwordx4 v[218:219], off
	v_lshl_add_u64 v[218:219], v[218:219], 0, s[6:7]
	s_waitcnt lgkmcnt(0)
	v_mfma_f32_32x32x16_bf16 v[112:127], v[188:191], v[156:159], v[112:127]
	ds_read_b128 v[200:203], v209
	ds_read_b128 v[172:175], v199
	v_mfma_f32_32x32x16_bf16 v[96:111], v[192:195], v[156:159], v[96:111]
	ds_read_b128 v[204:207], v209 offset:2048
	ds_read_b128 v[176:179], v199 offset:2048
	v_mfma_f32_32x32x16_bf16 v[80:95], v[188:191], v[160:163], v[80:95]
	ds_read_b128 v[180:183], v199 offset:4096
	ds_read_b128 v[184:187], v199 offset:6144
	v_mfma_f32_32x32x16_bf16 v[64:79], v[192:195], v[160:163], v[64:79]
	s_add_u32 m0, s21, 0xa000
	s_nop 0
	global_load_lds_dwordx4 v[216:217], off
	v_lshl_add_u64 v[216:217], v[216:217], 0, s[6:7]
	v_mfma_f32_32x32x16_bf16 v[48:63], v[188:191], v[164:167], v[48:63]
	v_mfma_f32_32x32x16_bf16 v[32:47], v[192:195], v[164:167], v[32:47]
	v_mfma_f32_32x32x16_bf16 v[16:31], v[188:191], v[168:171], v[16:31]
	v_mfma_f32_32x32x16_bf16 v[0:15], v[192:195], v[168:171], v[0:15]
	s_add_u32 m0, s21, 0xe000
	s_nop 0
	global_load_lds_dwordx4 v[220:221], off
	v_lshl_add_u64 v[220:221], v[220:221], 0, s[6:7]
	s_waitcnt lgkmcnt(0)
	s_waitcnt vmcnt(12)
	s_barrier
; #define G_LOADA(kt_) { _Pragma("unroll") for (int i = 0; i < 4; ++i) ra[i] = al(lrow + 64 * i, (kt_) * 64 + lck * 8); }
; #define G_LOADB(kt_) { _Pragma("unroll") for (int i = 0; i < 4; ++i) rb[i] = bl(lrow + 64 * i, (kt_) * 64 + lck * 8); }
; #define G_STOREA(buf_) { bf16_t* nA = sA + (buf_) * 256 * GLD; _Pragma("unroll") for (int i = 0; i < 4; ++i) *(u32x4*)(nA + (lrow + 64 * i) * GLD + lck * 8) = ra[i]; }
; #define G_STOREB(buf_) { bf16_t* nB = sB + (buf_) * 256 * GLD; _Pragma("unroll") for (int i = 0; i < 4; ++i) *(u32x4*)(nB + (lrow + 64 * i) * GLD + lck * 8) = rb[i]; }
; template <class AL, class BL, class EP>
; DI void gemm_tile256(AL al, BL bl, EP ep, int K, char* smem) {
;     ...
;   G_LOADA(0); G_LOADB(0);
;   __syncthreads();
;   G_STOREA(0); G_STOREB(0);
;   if (KT > 1) G_LOADB(1);
;   __syncthreads();
;   for (int kt = 0; kt < KT; kt += 2) {
;     G_STEP(0, kt);
;     if (kt + 1 >= KT) break;
;     G_STEP(1, kt + 1);
;   }
	s_waitcnt lgkmcnt(0)
	v_mfma_f32_32x32x16_bf16 v[112:127], v[200:203], v[172:175], v[112:127]
	ds_read_b128 v[188:191], v208 offset:32768
	ds_read_b128 v[156:159], v198 offset:32768
	v_mfma_f32_32x32x16_bf16 v[96:111], v[204:207], v[172:175], v[96:111]
	ds_read_b128 v[192:195], v208 offset:34816
	ds_read_b128 v[160:163], v198 offset:34816
	v_mfma_f32_32x32x16_bf16 v[80:95], v[200:203], v[176:179], v[80:95]
	ds_read_b128 v[164:167], v198 offset:36864
	ds_read_b128 v[168:171], v198 offset:38912
	v_mfma_f32_32x32x16_bf16 v[64:79], v[204:207], v[176:179], v[64:79]
	v_mfma_f32_32x32x16_bf16 v[48:63], v[200:203], v[180:183], v[48:63]
	v_mfma_f32_32x32x16_bf16 v[32:47], v[204:207], v[180:183], v[32:47]
	v_mfma_f32_32x32x16_bf16 v[16:31], v[200:203], v[184:187], v[16:31]
	v_mfma_f32_32x32x16_bf16 v[0:15], v[204:207], v[184:187], v[0:15]
	s_waitcnt lgkmcnt(0)
	v_mfma_f32_32x32x16_bf16 v[112:127], v[188:191], v[156:159], v[112:127]
	ds_read_b128 v[200:203], v209 offset:32768
	ds_read_b128 v[172:175], v199 offset:32768
	v_mfma_f32_32x32x16_bf16 v[96:111], v[192:195], v[156:159], v[96:111]
	ds_read_b128 v[204:207], v209 offset:34816
	ds_read_b128 v[176:179], v199 offset:34816
	v_mfma_f32_32x32x16_bf16 v[80:95], v[188:191], v[160:163], v[80:95]
	ds_read_b128 v[180:183], v199 offset:36864
	ds_read_b128 v[184:187], v199 offset:38912
	v_mfma_f32_32x32x16_bf16 v[64:79], v[192:195], v[160:163], v[64:79]
	v_mfma_f32_32x32x16_bf16 v[48:63], v[188:191], v[164:167], v[48:63]
	v_mfma_f32_32x32x16_bf16 v[32:47], v[192:195], v[164:167], v[32:47]
	v_mfma_f32_32x32x16_bf16 v[16:31], v[188:191], v[168:171], v[16:31]
	v_mfma_f32_32x32x16_bf16 v[0:15], v[192:195], v[168:171], v[0:15]
	s_waitcnt lgkmcnt(0)
	s_waitcnt vmcnt(8)
	s_barrier
	s_waitcnt lgkmcnt(0)
	v_mfma_f32_32x32x16_bf16 v[112:127], v[200:203], v[172:175], v[112:127]
	ds_read_b128 v[188:191], v212
	ds_read_b128 v[156:159], v210
	v_mfma_f32_32x32x16_bf16 v[96:111], v[204:207], v[172:175], v[96:111]
	ds_read_b128 v[192:195], v212 offset:2048
	ds_read_b128 v[160:163], v210 offset:2048
	v_mfma_f32_32x32x16_bf16 v[80:95], v[200:203], v[176:179], v[80:95]
	ds_read_b128 v[164:167], v210 offset:4096
	ds_read_b128 v[168:171], v210 offset:6144
	v_mfma_f32_32x32x16_bf16 v[64:79], v[204:207], v[176:179], v[64:79]
	v_mfma_f32_32x32x16_bf16 v[48:63], v[200:203], v[180:183], v[48:63]
	v_mfma_f32_32x32x16_bf16 v[32:47], v[204:207], v[180:183], v[32:47]
	v_mfma_f32_32x32x16_bf16 v[16:31], v[200:203], v[184:187], v[16:31]
	v_mfma_f32_32x32x16_bf16 v[0:15], v[204:207], v[184:187], v[0:15]
	s_waitcnt lgkmcnt(0)
	v_mfma_f32_32x32x16_bf16 v[112:127], v[188:191], v[156:159], v[112:127]
	ds_read_b128 v[200:203], v213
	ds_read_b128 v[172:175], v211
	v_mfma_f32_32x32x16_bf16 v[96:111], v[192:195], v[156:159], v[96:111]
	ds_read_b128 v[204:207], v213 offset:2048
	ds_read_b128 v[176:179], v211 offset:2048
	v_mfma_f32_32x32x16_bf16 v[80:95], v[188:191], v[160:163], v[80:95]
	ds_read_b128 v[180:183], v211 offset:4096
	ds_read_b128 v[184:187], v211 offset:6144
	v_mfma_f32_32x32x16_bf16 v[64:79], v[192:195], v[160:163], v[64:79]
	v_mfma_f32_32x32x16_bf16 v[48:63], v[188:191], v[164:167], v[48:63]
	v_mfma_f32_32x32x16_bf16 v[32:47], v[192:195], v[164:167], v[32:47]
	v_mfma_f32_32x32x16_bf16 v[16:31], v[188:191], v[168:171], v[16:31]
	v_mfma_f32_32x32x16_bf16 v[0:15], v[192:195], v[168:171], v[0:15]
	s_waitcnt lgkmcnt(0)
	s_waitcnt vmcnt(4)
	s_barrier
	s_waitcnt lgkmcnt(0)
	v_mfma_f32_32x32x16_bf16 v[112:127], v[200:203], v[172:175], v[112:127]
	ds_read_b128 v[188:191], v154
	ds_read_b128 v[156:159], v132
	v_mfma_f32_32x32x16_bf16 v[96:111], v[204:207], v[172:175], v[96:111]
	ds_read_b128 v[192:195], v154 offset:2048
	ds_read_b128 v[160:163], v132 offset:2048
	v_mfma_f32_32x32x16_bf16 v[80:95], v[200:203], v[176:179], v[80:95]
	ds_read_b128 v[164:167], v132 offset:4096
	ds_read_b128 v[168:171], v132 offset:6144
	v_mfma_f32_32x32x16_bf16 v[64:79], v[204:207], v[176:179], v[64:79]
	v_mfma_f32_32x32x16_bf16 v[48:63], v[200:203], v[180:183], v[48:63]
	v_mfma_f32_32x32x16_bf16 v[32:47], v[204:207], v[180:183], v[32:47]
	v_mfma_f32_32x32x16_bf16 v[16:31], v[200:203], v[184:187], v[16:31]
	v_mfma_f32_32x32x16_bf16 v[0:15], v[204:207], v[184:187], v[0:15]
	s_waitcnt lgkmcnt(0)
	v_mfma_f32_32x32x16_bf16 v[112:127], v[188:191], v[156:159], v[112:127]
	ds_read_b128 v[200:203], v155
	ds_read_b128 v[172:175], v153
	v_mfma_f32_32x32x16_bf16 v[96:111], v[192:195], v[156:159], v[96:111]
	ds_read_b128 v[204:207], v155 offset:2048
	ds_read_b128 v[176:179], v153 offset:2048
	v_mfma_f32_32x32x16_bf16 v[80:95], v[188:191], v[160:163], v[80:95]
	ds_read_b128 v[180:183], v153 offset:4096
	ds_read_b128 v[184:187], v153 offset:6144
	v_mfma_f32_32x32x16_bf16 v[64:79], v[192:195], v[160:163], v[64:79]
	v_mfma_f32_32x32x16_bf16 v[48:63], v[188:191], v[164:167], v[48:63]
	v_mfma_f32_32x32x16_bf16 v[32:47], v[192:195], v[164:167], v[32:47]
	v_mfma_f32_32x32x16_bf16 v[16:31], v[188:191], v[168:171], v[16:31]
	v_mfma_f32_32x32x16_bf16 v[0:15], v[192:195], v[168:171], v[0:15]
	s_waitcnt lgkmcnt(0)
	s_waitcnt vmcnt(0)
	s_barrier
; DI unsigned pack2(float a, float b) { f2_t f = {a, b}; bf2_t r = __builtin_convertvector(f, bf2_t); return __builtin_bit_cast(unsigned, r); }
; template <class AL, class BL, class EP>
; DI void gemm_tile256(AL al, BL bl, EP ep, int K, char* smem) {
;     ...
;   if constexpr (EP::kBf16) {
;     bf16_t* sCb = (bf16_t*)smem;
; #pragma unroll
;     for (int i = 0; i < 4; ++i)
; #pragma unroll
;       for (int j = 0; j < 2; ++j)
; #pragma unroll
;         for (int g = 0; g < 4; ++g) {
;           u32x2 v = {pack2(acc[i][j][4 * g], acc[i][j][4 * g + 1]), pack2(acc[i][j][4 * g + 2], acc[i][j][4 * g + 3])};
;           *(u32x2*)(sCb + (128 * wm + 32 * i + r) * BLD + 64 * wn + 32 * j + 8 * g + 4 * h) = v;
;         }
;     __syncthreads();
	s_waitcnt lgkmcnt(0)
	v_mfma_f32_32x32x16_bf16 v[112:127], v[200:203], v[172:175], v[112:127]
	ds_read_b128 v[188:191], v154 offset:32768
	ds_read_b128 v[156:159], v132 offset:32768
	v_mfma_f32_32x32x16_bf16 v[96:111], v[204:207], v[172:175], v[96:111]
	ds_read_b128 v[192:195], v154 offset:34816
	ds_read_b128 v[160:163], v132 offset:34816
	v_mfma_f32_32x32x16_bf16 v[80:95], v[200:203], v[176:179], v[80:95]
	ds_read_b128 v[164:167], v132 offset:36864
	ds_read_b128 v[168:171], v132 offset:38912
	v_mfma_f32_32x32x16_bf16 v[64:79], v[204:207], v[176:179], v[64:79]
	v_mfma_f32_32x32x16_bf16 v[48:63], v[200:203], v[180:183], v[48:63]
	v_mfma_f32_32x32x16_bf16 v[32:47], v[204:207], v[180:183], v[32:47]
	v_mfma_f32_32x32x16_bf16 v[16:31], v[200:203], v[184:187], v[16:31]
	v_mfma_f32_32x32x16_bf16 v[0:15], v[204:207], v[184:187], v[0:15]
	s_waitcnt lgkmcnt(0)
	v_mfma_f32_32x32x16_bf16 v[112:127], v[188:191], v[156:159], v[112:127]
	ds_read_b128 v[200:203], v155 offset:32768
	ds_read_b128 v[172:175], v153 offset:32768
	v_mfma_f32_32x32x16_bf16 v[96:111], v[192:195], v[156:159], v[96:111]
	ds_read_b128 v[204:207], v155 offset:34816
	ds_read_b128 v[176:179], v153 offset:34816
	v_mfma_f32_32x32x16_bf16 v[80:95], v[188:191], v[160:163], v[80:95]
	ds_read_b128 v[180:183], v153 offset:36864
	ds_read_b128 v[184:187], v153 offset:38912
	v_mfma_f32_32x32x16_bf16 v[64:79], v[192:195], v[160:163], v[64:79]
	v_mfma_f32_32x32x16_bf16 v[48:63], v[188:191], v[164:167], v[48:63]
	v_mfma_f32_32x32x16_bf16 v[32:47], v[192:195], v[164:167], v[32:47]
	v_mfma_f32_32x32x16_bf16 v[16:31], v[188:191], v[168:171], v[16:31]
	v_mfma_f32_32x32x16_bf16 v[0:15], v[192:195], v[168:171], v[0:15]
	s_waitcnt lgkmcnt(0)
	s_waitcnt lgkmcnt(0)
	v_mfma_f32_32x32x16_bf16 v[112:127], v[200:203], v[172:175], v[112:127]
	v_mfma_f32_32x32x16_bf16 v[96:111], v[204:207], v[172:175], v[96:111]
	v_mfma_f32_32x32x16_bf16 v[80:95], v[200:203], v[176:179], v[80:95]
	v_mfma_f32_32x32x16_bf16 v[64:79], v[204:207], v[176:179], v[64:79]
	v_mfma_f32_32x32x16_bf16 v[48:63], v[200:203], v[180:183], v[48:63]
	v_mfma_f32_32x32x16_bf16 v[32:47], v[204:207], v[180:183], v[32:47]
	v_mfma_f32_32x32x16_bf16 v[16:31], v[200:203], v[184:187], v[16:31]
	v_mfma_f32_32x32x16_bf16 v[0:15], v[204:207], v[184:187], v[0:15]
	s_nop 15
	s_nop 3
	v_lshl_or_b32 v128, v133, 7, v152
	s_waitcnt lgkmcnt(4)
	v_mad_u64_u32 v[130:131], s[4:5], v151, s46, v[128:129]
	s_and_b32 s24, s52, 0xf00
	s_waitcnt lgkmcnt(0)
	s_barrier
	s_cmp_gt_i32 s20, 3
	s_nop 5
	v_cvt_pk_bf16_f32 v112, v112, v113
	v_cvt_pk_bf16_f32 v113, v114, v115
	v_cvt_pk_bf16_f32 v114, v116, v117
	v_cvt_pk_bf16_f32 v115, v118, v119
	ds_write2_b64 v130, v[112:113], v[114:115] offset1:2
	v_cvt_pk_bf16_f32 v112, v120, v121
	v_cvt_pk_bf16_f32 v113, v122, v123
	v_cvt_pk_bf16_f32 v96, v96, v97
	v_cvt_pk_bf16_f32 v97, v98, v99
	v_cvt_pk_bf16_f32 v98, v100, v101
	v_cvt_pk_bf16_f32 v99, v102, v103
	v_cvt_pk_bf16_f32 v114, v124, v125
	v_cvt_pk_bf16_f32 v115, v126, v127
	ds_write2_b64 v130, v[96:97], v[98:99] offset0:8 offset1:10
	s_nop 3
	v_cvt_pk_bf16_f32 v80, v80, v81
	v_cvt_pk_bf16_f32 v81, v82, v83
	v_cvt_pk_bf16_f32 v82, v84, v85
	v_cvt_pk_bf16_f32 v83, v86, v87
	v_add_u32_e32 v84, 0x4000, v130
	v_cvt_pk_bf16_f32 v96, v104, v105
	v_cvt_pk_bf16_f32 v97, v106, v107
	v_cvt_pk_bf16_f32 v64, v64, v65
	v_cvt_pk_bf16_f32 v65, v66, v67
	v_cvt_pk_bf16_f32 v66, v68, v69
	v_cvt_pk_bf16_f32 v67, v70, v71
	v_cvt_pk_bf16_f32 v98, v108, v109
	v_cvt_pk_bf16_f32 v99, v110, v111
	ds_write2_b64 v84, v[80:81], v[82:83] offset0:64 offset1:66
	s_nop 3
	v_cvt_pk_bf16_f32 v48, v48, v49
	v_cvt_pk_bf16_f32 v49, v50, v51
	v_cvt_pk_bf16_f32 v50, v52, v53
	v_cvt_pk_bf16_f32 v51, v54, v55
	v_add_u32_e32 v52, 0x8000, v130
	v_cvt_pk_bf16_f32 v80, v88, v89
	v_cvt_pk_bf16_f32 v81, v90, v91
	v_cvt_pk_bf16_f32 v32, v32, v33
	v_cvt_pk_bf16_f32 v33, v34, v35
	v_cvt_pk_bf16_f32 v34, v36, v37
	v_cvt_pk_bf16_f32 v35, v38, v39
	v_cvt_pk_bf16_f32 v82, v92, v93
	v_cvt_pk_bf16_f32 v83, v94, v95
	ds_write2_b64 v84, v[64:65], v[66:67] offset0:72 offset1:74
	s_nop 3
	v_cvt_pk_bf16_f32 v16, v16, v17
	v_cvt_pk_bf16_f32 v17, v18, v19
	v_cvt_pk_bf16_f32 v18, v20, v21
	v_cvt_pk_bf16_f32 v19, v22, v23
	v_add_u32_e32 v20, 0xc000, v130
	v_cvt_pk_bf16_f32 v64, v72, v73
	v_cvt_pk_bf16_f32 v65, v74, v75
	s_nop 0
	v_cvt_pk_bf16_f32 v0, v0, v1
	v_cvt_pk_bf16_f32 v1, v2, v3
	v_cvt_pk_bf16_f32 v2, v4, v5
	v_cvt_pk_bf16_f32 v3, v6, v7
	v_cvt_pk_bf16_f32 v66, v76, v77
	v_cvt_pk_bf16_f32 v67, v78, v79
	ds_write2_b64 v52, v[48:49], v[50:51] offset0:128 offset1:130
	v_cvt_pk_bf16_f32 v48, v56, v57
	v_cvt_pk_bf16_f32 v49, v58, v59
	v_cvt_pk_bf16_f32 v50, v60, v61
	v_cvt_pk_bf16_f32 v51, v62, v63
	ds_write2_b64 v52, v[32:33], v[34:35] offset0:136 offset1:138
	v_cvt_pk_bf16_f32 v32, v40, v41
	v_cvt_pk_bf16_f32 v33, v42, v43
	v_cvt_pk_bf16_f32 v34, v44, v45
	v_cvt_pk_bf16_f32 v35, v46, v47
	ds_write2_b64 v20, v[16:17], v[18:19] offset0:192 offset1:194
	v_cvt_pk_bf16_f32 v16, v24, v25
	v_cvt_pk_bf16_f32 v17, v26, v27
	v_cvt_pk_bf16_f32 v18, v28, v29
	v_cvt_pk_bf16_f32 v19, v30, v31
	ds_write2_b64 v20, v[0:1], v[2:3] offset0:200 offset1:202
	v_cvt_pk_bf16_f32 v0, v8, v9
	v_cvt_pk_bf16_f32 v1, v10, v11
	v_cvt_pk_bf16_f32 v2, v12, v13
	v_cvt_pk_bf16_f32 v3, v14, v15
	ds_write2_b64 v130, v[112:113], v[114:115] offset0:4 offset1:6
	ds_write2_b64 v130, v[96:97], v[98:99] offset0:12 offset1:14
	ds_write2_b64 v84, v[80:81], v[82:83] offset0:68 offset1:70
	ds_write2_b64 v84, v[64:65], v[66:67] offset0:76 offset1:78
	ds_write2_b64 v52, v[48:49], v[50:51] offset0:132 offset1:134
	ds_write2_b64 v52, v[32:33], v[34:35] offset0:140 offset1:142
	ds_write2_b64 v20, v[16:17], v[18:19] offset0:196 offset1:198
	ds_write2_b64 v20, v[0:1], v[2:3] offset0:204 offset1:206
	s_waitcnt lgkmcnt(0)
	s_barrier
; DI float bf2f(bf16_t v) { return __uint_as_float(((unsigned)v) << 16); }
; DI bf16_t f2bf(float x) { return (bf16_t)(pack2(x, 0.f) & 0xffffu); }
; DI int tid512() { int t = threadIdx_x_raw(); asm volatile("" : "+v"(t)); return t; }
;   DI void operator()(bf16_t* sCb) const {
;     ...
;     if (nt2 < 4) {
;       const float2* rope = (const float2*)(ws + OFF_ROPER);
;       const float sc = (nt2 >= 2) ? 0.08838834764831845f : 1.f;
;       for (int id = tid512(); id < 256 * 128; id += 512) {
;         int row = id >> 7, hf = (id >> 6) & 1, i = id & 63;
;         float2 cs = rope[(size_t)(s0 + row) * 64 + i];
;         bf16_t* q1 = sCb + row * BLD + 128 * hf + i;
;         float x1 = bf2f(q1[0]), x2 = bf2f(q1[64]);
;         q1[0] = f2bf((x1 * cs.x - x2 * cs.y) * sc);
;         q1[64] = f2bf((x1 * cs.y + x2 * cs.x) * sc);
;       }
	s_cbranch_scc1 .LBB0_771
	v_mov_b32_e32 v2, v196
	s_nop 0
	v_cmp_gt_i32_e32 vcc, s47, v2
	s_and_saveexec_b64 s[4:5], vcc
	s_cbranch_execz .LBB0_770
	s_cmp_gt_i32 s20, 1
	v_and_b32_e32 v4, 63, v196
	s_cselect_b64 vcc, -1, 0
	v_lshrrev_b32_e32 v8, 7, v196
	v_cndmask_b32_e32 v3, 1.0, v150, vcc
	v_mul_lo_u32 v12, v8, s46
	v_lshlrev_b32_e32 v13, 1, v196
	v_and_b32_e32 v13, 0x80, v13
	v_lshlrev_b32_e32 v13, 1, v13
	v_lshlrev_b32_e32 v14, 1, v4
	v_add3_u32 v12, v12, v13, v14
	v_add_u32_e32 v15, s24, v8
	v_lshlrev_b32_e32 v15, 9, v15
	v_lshl_add_u32 v16, v4, 3, v15
	v_add_u32_e32 v17, 0x1000, v16
	v_add_u32_e32 v18, 0x2000, v16
	v_add_u32_e32 v19, 0x3000, v16
	v_add_u32_e32 v20, 0x4000, v16
	v_add_u32_e32 v21, 0x5000, v16
	v_add_u32_e32 v22, 0x6000, v16
	v_add_u32_e32 v23, 0x7000, v16
	s_lshl_b32 s10, s46, 2
	global_load_dwordx2 v[200:201], v16, s[2:3]
	global_load_dwordx2 v[202:203], v16, s[2:3] offset:2048
	global_load_dwordx2 v[204:205], v17, s[2:3]
	global_load_dwordx2 v[206:207], v17, s[2:3] offset:2048
	global_load_dwordx2 v[208:209], v18, s[2:3]
	global_load_dwordx2 v[210:211], v18, s[2:3] offset:2048
	global_load_dwordx2 v[212:213], v19, s[2:3]
	global_load_dwordx2 v[214:215], v19, s[2:3] offset:2048
	global_load_dwordx2 v[216:217], v20, s[2:3]
	global_load_dwordx2 v[218:219], v20, s[2:3] offset:2048
	global_load_dwordx2 v[220:221], v21, s[2:3]
	global_load_dwordx2 v[222:223], v21, s[2:3] offset:2048
	global_load_dwordx2 v[224:225], v22, s[2:3]
	global_load_dwordx2 v[226:227], v22, s[2:3] offset:2048
	global_load_dwordx2 v[228:229], v23, s[2:3]
	global_load_dwordx2 v[230:231], v23, s[2:3] offset:2048
	ds_read_u16 v9, v12
	ds_read_u16 v10, v12 offset:128
	v_add_u32_e32 v26, s10, v12
	ds_read_u16 v24, v26
	ds_read_u16 v25, v26 offset:128
	s_waitcnt vmcnt(15) lgkmcnt(2)
	v_lshlrev_b32_e32 v9, 16, v9
	v_lshlrev_b32_e32 v10, 16, v10
	v_mul_f32_e32 v11, v201, v10
	v_mul_f32_e32 v10, v200, v10
	v_fma_f32 v6, v200, v9, -v11
	v_fmac_f32_e32 v10, v201, v9
	v_mul_f32_e32 v6, v3, v6
	v_mul_f32_e32 v7, v3, v10
	v_cvt_pk_bf16_f32 v6, v6, s0
	v_cvt_pk_bf16_f32 v7, v7, s0
	ds_write_b16 v12, v6
	ds_write_b16 v12, v7 offset:128
	v_add_u32_e32 v16, 0x8000, v16
	global_load_dwordx2 v[200:201], v16, s[2:3]
	v_add_u32_e32 v12, s10, v12
	v_add_u32_e32 v26, s10, v12
	ds_read_u16 v9, v26
	ds_read_u16 v10, v26 offset:128
	s_waitcnt vmcnt(15) lgkmcnt(4)
	v_lshlrev_b32_e32 v24, 16, v24
	v_lshlrev_b32_e32 v25, 16, v25
	v_mul_f32_e32 v11, v203, v25
	v_mul_f32_e32 v25, v202, v25
	v_fma_f32 v6, v202, v24, -v11
	v_fmac_f32_e32 v25, v203, v24
	v_mul_f32_e32 v6, v3, v6
	v_mul_f32_e32 v7, v3, v25
	v_cvt_pk_bf16_f32 v6, v6, s0
	v_cvt_pk_bf16_f32 v7, v7, s0
	ds_write_b16 v12, v6
	ds_write_b16 v12, v7 offset:128
	global_load_dwordx2 v[202:203], v16, s[2:3] offset:2048
	v_add_u32_e32 v12, s10, v12
	v_add_u32_e32 v26, s10, v12
	ds_read_u16 v24, v26
	ds_read_u16 v25, v26 offset:128
	s_waitcnt vmcnt(15) lgkmcnt(4)
	v_lshlrev_b32_e32 v9, 16, v9
	v_lshlrev_b32_e32 v10, 16, v10
	v_mul_f32_e32 v11, v205, v10
	v_mul_f32_e32 v10, v204, v10
	v_fma_f32 v6, v204, v9, -v11
	v_fmac_f32_e32 v10, v205, v9
	v_mul_f32_e32 v6, v3, v6
	v_mul_f32_e32 v7, v3, v10
	v_cvt_pk_bf16_f32 v6, v6, s0
	v_cvt_pk_bf16_f32 v7, v7, s0
	ds_write_b16 v12, v6
	ds_write_b16 v12, v7 offset:128
	v_add_u32_e32 v17, 0x8000, v17
	global_load_dwordx2 v[204:205], v17, s[2:3]
	v_add_u32_e32 v12, s10, v12
	v_add_u32_e32 v26, s10, v12
	ds_read_u16 v9, v26
	ds_read_u16 v10, v26 offset:128
	s_waitcnt vmcnt(15) lgkmcnt(4)
	v_lshlrev_b32_e32 v24, 16, v24
	v_lshlrev_b32_e32 v25, 16, v25
	v_mul_f32_e32 v11, v207, v25
	v_mul_f32_e32 v25, v206, v25
	v_fma_f32 v6, v206, v24, -v11
	v_fmac_f32_e32 v25, v207, v24
	v_mul_f32_e32 v6, v3, v6
	v_mul_f32_e32 v7, v3, v25
	v_cvt_pk_bf16_f32 v6, v6, s0
	v_cvt_pk_bf16_f32 v7, v7, s0
	ds_write_b16 v12, v6
	ds_write_b16 v12, v7 offset:128
	global_load_dwordx2 v[206:207], v17, s[2:3] offset:2048
	v_add_u32_e32 v12, s10, v12
	v_add_u32_e32 v26, s10, v12
	ds_read_u16 v24, v26
	ds_read_u16 v25, v26 offset:128
	s_waitcnt vmcnt(15) lgkmcnt(4)
	v_lshlrev_b32_e32 v9, 16, v9
	v_lshlrev_b32_e32 v10, 16, v10
	v_mul_f32_e32 v11, v209, v10
	v_mul_f32_e32 v10, v208, v10
	v_fma_f32 v6, v208, v9, -v11
	v_fmac_f32_e32 v10, v209, v9
	v_mul_f32_e32 v6, v3, v6
	v_mul_f32_e32 v7, v3, v10
	v_cvt_pk_bf16_f32 v6, v6, s0
	v_cvt_pk_bf16_f32 v7, v7, s0
	ds_write_b16 v12, v6
	ds_write_b16 v12, v7 offset:128
	v_add_u32_e32 v18, 0x8000, v18
	global_load_dwordx2 v[208:209], v18, s[2:3]
	v_add_u32_e32 v12, s10, v12
	v_add_u32_e32 v26, s10, v12
	ds_read_u16 v9, v26
	ds_read_u16 v10, v26 offset:128
	s_waitcnt vmcnt(15) lgkmcnt(4)
	v_lshlrev_b32_e32 v24, 16, v24
	v_lshlrev_b32_e32 v25, 16, v25
	v_mul_f32_e32 v11, v211, v25
	v_mul_f32_e32 v25, v210, v25
	v_fma_f32 v6, v210, v24, -v11
	v_fmac_f32_e32 v25, v211, v24
	v_mul_f32_e32 v6, v3, v6
	v_mul_f32_e32 v7, v3, v25
	v_cvt_pk_bf16_f32 v6, v6, s0
	v_cvt_pk_bf16_f32 v7, v7, s0
	ds_write_b16 v12, v6
	ds_write_b16 v12, v7 offset:128
	global_load_dwordx2 v[210:211], v18, s[2:3] offset:2048
	v_add_u32_e32 v12, s10, v12
	v_add_u32_e32 v26, s10, v12
	ds_read_u16 v24, v26
	ds_read_u16 v25, v26 offset:128
	s_waitcnt vmcnt(15) lgkmcnt(4)
	v_lshlrev_b32_e32 v9, 16, v9
	v_lshlrev_b32_e32 v10, 16, v10
	v_mul_f32_e32 v11, v213, v10
	v_mul_f32_e32 v10, v212, v10
	v_fma_f32 v6, v212, v9, -v11
	v_fmac_f32_e32 v10, v213, v9
	v_mul_f32_e32 v6, v3, v6
	v_mul_f32_e32 v7, v3, v10
	v_cvt_pk_bf16_f32 v6, v6, s0
	v_cvt_pk_bf16_f32 v7, v7, s0
	ds_write_b16 v12, v6
	ds_write_b16 v12, v7 offset:128
	v_add_u32_e32 v19, 0x8000, v19
	global_load_dwordx2 v[212:213], v19, s[2:3]
	v_add_u32_e32 v12, s10, v12
	v_add_u32_e32 v26, s10, v12
	ds_read_u16 v9, v26
	ds_read_u16 v10, v26 offset:128
	s_waitcnt vmcnt(15) lgkmcnt(4)
; DI float bf2f(bf16_t v) { return __uint_as_float(((unsigned)v) << 16); }
; DI bf16_t f2bf(float x) { return (bf16_t)(pack2(x, 0.f) & 0xffffu); }
; DI int tid512() { int t = threadIdx_x_raw(); asm volatile("" : "+v"(t)); return t; }
;   DI void operator()(bf16_t* sCb) const {
;     ...
;       for (int id = tid512(); id < 256 * 128; id += 512) {
;         int row = id >> 7, hf = (id >> 6) & 1, i = id & 63;
;         float2 cs = rope[(size_t)(s0 + row) * 64 + i];
;         bf16_t* q1 = sCb + row * BLD + 128 * hf + i;
;         float x1 = bf2f(q1[0]), x2 = bf2f(q1[64]);
;         q1[0] = f2bf((x1 * cs.x - x2 * cs.y) * sc);
;         q1[64] = f2bf((x1 * cs.y + x2 * cs.x) * sc);
;       }
	v_lshlrev_b32_e32 v24, 16, v24
	v_lshlrev_b32_e32 v25, 16, v25
	v_mul_f32_e32 v11, v215, v25
	v_mul_f32_e32 v25, v214, v25
	v_fma_f32 v6, v214, v24, -v11
	v_fmac_f32_e32 v25, v215, v24
	v_mul_f32_e32 v6, v3, v6
	v_mul_f32_e32 v7, v3, v25
	v_cvt_pk_bf16_f32 v6, v6, s0
	v_cvt_pk_bf16_f32 v7, v7, s0
	ds_write_b16 v12, v6
	ds_write_b16 v12, v7 offset:128
	global_load_dwordx2 v[214:215], v19, s[2:3] offset:2048
	v_add_u32_e32 v12, s10, v12
	v_add_u32_e32 v26, s10, v12
	ds_read_u16 v24, v26
	ds_read_u16 v25, v26 offset:128
	s_waitcnt vmcnt(15) lgkmcnt(4)
	v_lshlrev_b32_e32 v9, 16, v9
	v_lshlrev_b32_e32 v10, 16, v10
	v_mul_f32_e32 v11, v217, v10
	v_mul_f32_e32 v10, v216, v10
	v_fma_f32 v6, v216, v9, -v11
	v_fmac_f32_e32 v10, v217, v9
	v_mul_f32_e32 v6, v3, v6
	v_mul_f32_e32 v7, v3, v10
	v_cvt_pk_bf16_f32 v6, v6, s0
	v_cvt_pk_bf16_f32 v7, v7, s0
	ds_write_b16 v12, v6
	ds_write_b16 v12, v7 offset:128
	v_add_u32_e32 v20, 0x8000, v20
	global_load_dwordx2 v[216:217], v20, s[2:3]
	v_add_u32_e32 v12, s10, v12
	v_add_u32_e32 v26, s10, v12
	ds_read_u16 v9, v26
	ds_read_u16 v10, v26 offset:128
	s_waitcnt vmcnt(15) lgkmcnt(4)
	v_lshlrev_b32_e32 v24, 16, v24
	v_lshlrev_b32_e32 v25, 16, v25
	v_mul_f32_e32 v11, v219, v25
	v_mul_f32_e32 v25, v218, v25
	v_fma_f32 v6, v218, v24, -v11
	v_fmac_f32_e32 v25, v219, v24
	v_mul_f32_e32 v6, v3, v6
	v_mul_f32_e32 v7, v3, v25
	v_cvt_pk_bf16_f32 v6, v6, s0
	v_cvt_pk_bf16_f32 v7, v7, s0
	ds_write_b16 v12, v6
	ds_write_b16 v12, v7 offset:128
	global_load_dwordx2 v[218:219], v20, s[2:3] offset:2048
	v_add_u32_e32 v12, s10, v12
	v_add_u32_e32 v26, s10, v12
	ds_read_u16 v24, v26
	ds_read_u16 v25, v26 offset:128
	s_waitcnt vmcnt(15) lgkmcnt(4)
	v_lshlrev_b32_e32 v9, 16, v9
	v_lshlrev_b32_e32 v10, 16, v10
	v_mul_f32_e32 v11, v221, v10
	v_mul_f32_e32 v10, v220, v10
	v_fma_f32 v6, v220, v9, -v11
	v_fmac_f32_e32 v10, v221, v9
	v_mul_f32_e32 v6, v3, v6
	v_mul_f32_e32 v7, v3, v10
	v_cvt_pk_bf16_f32 v6, v6, s0
	v_cvt_pk_bf16_f32 v7, v7, s0
	ds_write_b16 v12, v6
	ds_write_b16 v12, v7 offset:128
	v_add_u32_e32 v21, 0x8000, v21
	global_load_dwordx2 v[220:221], v21, s[2:3]
	v_add_u32_e32 v12, s10, v12
	v_add_u32_e32 v26, s10, v12
	ds_read_u16 v9, v26
	ds_read_u16 v10, v26 offset:128
	s_waitcnt vmcnt(15) lgkmcnt(4)
	v_lshlrev_b32_e32 v24, 16, v24
	v_lshlrev_b32_e32 v25, 16, v25
	v_mul_f32_e32 v11, v223, v25
	v_mul_f32_e32 v25, v222, v25
	v_fma_f32 v6, v222, v24, -v11
	v_fmac_f32_e32 v25, v223, v24
	v_mul_f32_e32 v6, v3, v6
	v_mul_f32_e32 v7, v3, v25
	v_cvt_pk_bf16_f32 v6, v6, s0
	v_cvt_pk_bf16_f32 v7, v7, s0
	ds_write_b16 v12, v6
	ds_write_b16 v12, v7 offset:128
	global_load_dwordx2 v[222:223], v21, s[2:3] offset:2048
	v_add_u32_e32 v12, s10, v12
	v_add_u32_e32 v26, s10, v12
	ds_read_u16 v24, v26
	ds_read_u16 v25, v26 offset:128
	s_waitcnt vmcnt(15) lgkmcnt(4)
	v_lshlrev_b32_e32 v9, 16, v9
	v_lshlrev_b32_e32 v10, 16, v10
	v_mul_f32_e32 v11, v225, v10
	v_mul_f32_e32 v10, v224, v10
	v_fma_f32 v6, v224, v9, -v11
	v_fmac_f32_e32 v10, v225, v9
	v_mul_f32_e32 v6, v3, v6
	v_mul_f32_e32 v7, v3, v10
	v_cvt_pk_bf16_f32 v6, v6, s0
	v_cvt_pk_bf16_f32 v7, v7, s0
	ds_write_b16 v12, v6
	ds_write_b16 v12, v7 offset:128
	v_add_u32_e32 v22, 0x8000, v22
	global_load_dwordx2 v[224:225], v22, s[2:3]
	v_add_u32_e32 v12, s10, v12
	v_add_u32_e32 v26, s10, v12
	ds_read_u16 v9, v26
	ds_read_u16 v10, v26 offset:128
	s_waitcnt vmcnt(15) lgkmcnt(4)
	v_lshlrev_b32_e32 v24, 16, v24
	v_lshlrev_b32_e32 v25, 16, v25
	v_mul_f32_e32 v11, v227, v25
	v_mul_f32_e32 v25, v226, v25
	v_fma_f32 v6, v226, v24, -v11
	v_fmac_f32_e32 v25, v227, v24
	v_mul_f32_e32 v6, v3, v6
	v_mul_f32_e32 v7, v3, v25
	v_cvt_pk_bf16_f32 v6, v6, s0
	v_cvt_pk_bf16_f32 v7, v7, s0
	ds_write_b16 v12, v6
	ds_write_b16 v12, v7 offset:128
	global_load_dwordx2 v[226:227], v22, s[2:3] offset:2048
	v_add_u32_e32 v12, s10, v12
	v_add_u32_e32 v26, s10, v12
	ds_read_u16 v24, v26
	ds_read_u16 v25, v26 offset:128
	s_waitcnt vmcnt(15) lgkmcnt(4)
	v_lshlrev_b32_e32 v9, 16, v9
	v_lshlrev_b32_e32 v10, 16, v10
	v_mul_f32_e32 v11, v229, v10
	v_mul_f32_e32 v10, v228, v10
	v_fma_f32 v6, v228, v9, -v11
	v_fmac_f32_e32 v10, v229, v9
	v_mul_f32_e32 v6, v3, v6
	v_mul_f32_e32 v7, v3, v10
	v_cvt_pk_bf16_f32 v6, v6, s0
	v_cvt_pk_bf16_f32 v7, v7, s0
	ds_write_b16 v12, v6
	ds_write_b16 v12, v7 offset:128
	v_add_u32_e32 v23, 0x8000, v23
	global_load_dwordx2 v[228:229], v23, s[2:3]
	v_add_u32_e32 v12, s10, v12
	v_add_u32_e32 v26, s10, v12
	ds_read_u16 v9, v26
	ds_read_u16 v10, v26 offset:128
	s_waitcnt vmcnt(15) lgkmcnt(4)
	v_lshlrev_b32_e32 v24, 16, v24
	v_lshlrev_b32_e32 v25, 16, v25
	v_mul_f32_e32 v11, v231, v25
	v_mul_f32_e32 v25, v230, v25
	v_fma_f32 v6, v230, v24, -v11
	v_fmac_f32_e32 v25, v231, v24
	v_mul_f32_e32 v6, v3, v6
	v_mul_f32_e32 v7, v3, v25
	v_cvt_pk_bf16_f32 v6, v6, s0
	v_cvt_pk_bf16_f32 v7, v7, s0
	ds_write_b16 v12, v6
	ds_write_b16 v12, v7 offset:128
	global_load_dwordx2 v[230:231], v23, s[2:3] offset:2048
	v_add_u32_e32 v12, s10, v12
	v_add_u32_e32 v26, s10, v12
	ds_read_u16 v24, v26
	ds_read_u16 v25, v26 offset:128
	s_waitcnt vmcnt(15) lgkmcnt(4)
	v_lshlrev_b32_e32 v9, 16, v9
	v_lshlrev_b32_e32 v10, 16, v10
	v_mul_f32_e32 v11, v201, v10
	v_mul_f32_e32 v10, v200, v10
	v_fma_f32 v6, v200, v9, -v11
	v_fmac_f32_e32 v10, v201, v9
	v_mul_f32_e32 v6, v3, v6
	v_mul_f32_e32 v7, v3, v10
	v_cvt_pk_bf16_f32 v6, v6, s0
	v_cvt_pk_bf16_f32 v7, v7, s0
	ds_write_b16 v12, v6
	ds_write_b16 v12, v7 offset:128
	v_add_u32_e32 v16, 0x8000, v16
	global_load_dwordx2 v[200:201], v16, s[2:3]
	v_add_u32_e32 v12, s10, v12
	v_add_u32_e32 v26, s10, v12
	ds_read_u16 v9, v26
	ds_read_u16 v10, v26 offset:128
	s_waitcnt vmcnt(15) lgkmcnt(4)
; DI float bf2f(bf16_t v) { return __uint_as_float(((unsigned)v) << 16); }
; DI bf16_t f2bf(float x) { return (bf16_t)(pack2(x, 0.f) & 0xffffu); }
; DI int tid512() { int t = threadIdx_x_raw(); asm volatile("" : "+v"(t)); return t; }
;   DI void operator()(bf16_t* sCb) const {
;     ...
;       for (int id = tid512(); id < 256 * 128; id += 512) {
;         int row = id >> 7, hf = (id >> 6) & 1, i = id & 63;
;         float2 cs = rope[(size_t)(s0 + row) * 64 + i];
;         bf16_t* q1 = sCb + row * BLD + 128 * hf + i;
;         float x1 = bf2f(q1[0]), x2 = bf2f(q1[64]);
;         q1[0] = f2bf((x1 * cs.x - x2 * cs.y) * sc);
;         q1[64] = f2bf((x1 * cs.y + x2 * cs.x) * sc);
;       }
	v_lshlrev_b32_e32 v24, 16, v24
	v_lshlrev_b32_e32 v25, 16, v25
	v_mul_f32_e32 v11, v203, v25
	v_mul_f32_e32 v25, v202, v25
	v_fma_f32 v6, v202, v24, -v11
	v_fmac_f32_e32 v25, v203, v24
	v_mul_f32_e32 v6, v3, v6
	v_mul_f32_e32 v7, v3, v25
	v_cvt_pk_bf16_f32 v6, v6, s0
	v_cvt_pk_bf16_f32 v7, v7, s0
	ds_write_b16 v12, v6
	ds_write_b16 v12, v7 offset:128
	global_load_dwordx2 v[202:203], v16, s[2:3] offset:2048
	v_add_u32_e32 v12, s10, v12
	v_add_u32_e32 v26, s10, v12
	ds_read_u16 v24, v26
	ds_read_u16 v25, v26 offset:128
	s_waitcnt vmcnt(15) lgkmcnt(4)
	v_lshlrev_b32_e32 v9, 16, v9
	v_lshlrev_b32_e32 v10, 16, v10
	v_mul_f32_e32 v11, v205, v10
	v_mul_f32_e32 v10, v204, v10
	v_fma_f32 v6, v204, v9, -v11
	v_fmac_f32_e32 v10, v205, v9
	v_mul_f32_e32 v6, v3, v6
	v_mul_f32_e32 v7, v3, v10
	v_cvt_pk_bf16_f32 v6, v6, s0
	v_cvt_pk_bf16_f32 v7, v7, s0
	ds_write_b16 v12, v6
	ds_write_b16 v12, v7 offset:128
	v_add_u32_e32 v17, 0x8000, v17
	global_load_dwordx2 v[204:205], v17, s[2:3]
	v_add_u32_e32 v12, s10, v12
	v_add_u32_e32 v26, s10, v12
	ds_read_u16 v9, v26
	ds_read_u16 v10, v26 offset:128
	s_waitcnt vmcnt(15) lgkmcnt(4)
	v_lshlrev_b32_e32 v24, 16, v24
	v_lshlrev_b32_e32 v25, 16, v25
	v_mul_f32_e32 v11, v207, v25
	v_mul_f32_e32 v25, v206, v25
	v_fma_f32 v6, v206, v24, -v11
	v_fmac_f32_e32 v25, v207, v24
	v_mul_f32_e32 v6, v3, v6
	v_mul_f32_e32 v7, v3, v25
	v_cvt_pk_bf16_f32 v6, v6, s0
	v_cvt_pk_bf16_f32 v7, v7, s0
	ds_write_b16 v12, v6
	ds_write_b16 v12, v7 offset:128
	global_load_dwordx2 v[206:207], v17, s[2:3] offset:2048
	v_add_u32_e32 v12, s10, v12
	v_add_u32_e32 v26, s10, v12
	ds_read_u16 v24, v26
	ds_read_u16 v25, v26 offset:128
	s_waitcnt vmcnt(15) lgkmcnt(4)
	v_lshlrev_b32_e32 v9, 16, v9
	v_lshlrev_b32_e32 v10, 16, v10
	v_mul_f32_e32 v11, v209, v10
	v_mul_f32_e32 v10, v208, v10
	v_fma_f32 v6, v208, v9, -v11
	v_fmac_f32_e32 v10, v209, v9
	v_mul_f32_e32 v6, v3, v6
	v_mul_f32_e32 v7, v3, v10
	v_cvt_pk_bf16_f32 v6, v6, s0
	v_cvt_pk_bf16_f32 v7, v7, s0
	ds_write_b16 v12, v6
	ds_write_b16 v12, v7 offset:128
	v_add_u32_e32 v18, 0x8000, v18
	global_load_dwordx2 v[208:209], v18, s[2:3]
	v_add_u32_e32 v12, s10, v12
	v_add_u32_e32 v26, s10, v12
	ds_read_u16 v9, v26
	ds_read_u16 v10, v26 offset:128
	s_waitcnt vmcnt(15) lgkmcnt(4)
	v_lshlrev_b32_e32 v24, 16, v24
	v_lshlrev_b32_e32 v25, 16, v25
	v_mul_f32_e32 v11, v211, v25
	v_mul_f32_e32 v25, v210, v25
	v_fma_f32 v6, v210, v24, -v11
	v_fmac_f32_e32 v25, v211, v24
	v_mul_f32_e32 v6, v3, v6
	v_mul_f32_e32 v7, v3, v25
	v_cvt_pk_bf16_f32 v6, v6, s0
	v_cvt_pk_bf16_f32 v7, v7, s0
	ds_write_b16 v12, v6
	ds_write_b16 v12, v7 offset:128
	global_load_dwordx2 v[210:211], v18, s[2:3] offset:2048
	v_add_u32_e32 v12, s10, v12
	v_add_u32_e32 v26, s10, v12
	ds_read_u16 v24, v26
	ds_read_u16 v25, v26 offset:128
	s_waitcnt vmcnt(15) lgkmcnt(4)
	v_lshlrev_b32_e32 v9, 16, v9
	v_lshlrev_b32_e32 v10, 16, v10
	v_mul_f32_e32 v11, v213, v10
	v_mul_f32_e32 v10, v212, v10
	v_fma_f32 v6, v212, v9, -v11
	v_fmac_f32_e32 v10, v213, v9
	v_mul_f32_e32 v6, v3, v6
	v_mul_f32_e32 v7, v3, v10
	v_cvt_pk_bf16_f32 v6, v6, s0
	v_cvt_pk_bf16_f32 v7, v7, s0
	ds_write_b16 v12, v6
	ds_write_b16 v12, v7 offset:128
	v_add_u32_e32 v19, 0x8000, v19
	global_load_dwordx2 v[212:213], v19, s[2:3]
	v_add_u32_e32 v12, s10, v12
	v_add_u32_e32 v26, s10, v12
	ds_read_u16 v9, v26
	ds_read_u16 v10, v26 offset:128
	s_waitcnt vmcnt(15) lgkmcnt(4)
	v_lshlrev_b32_e32 v24, 16, v24
	v_lshlrev_b32_e32 v25, 16, v25
	v_mul_f32_e32 v11, v215, v25
	v_mul_f32_e32 v25, v214, v25
	v_fma_f32 v6, v214, v24, -v11
	v_fmac_f32_e32 v25, v215, v24
	v_mul_f32_e32 v6, v3, v6
	v_mul_f32_e32 v7, v3, v25
	v_cvt_pk_bf16_f32 v6, v6, s0
	v_cvt_pk_bf16_f32 v7, v7, s0
	ds_write_b16 v12, v6
	ds_write_b16 v12, v7 offset:128
	global_load_dwordx2 v[214:215], v19, s[2:3] offset:2048
	v_add_u32_e32 v12, s10, v12
	v_add_u32_e32 v26, s10, v12
	ds_read_u16 v24, v26
	ds_read_u16 v25, v26 offset:128
	s_waitcnt vmcnt(15) lgkmcnt(4)
	v_lshlrev_b32_e32 v9, 16, v9
	v_lshlrev_b32_e32 v10, 16, v10
	v_mul_f32_e32 v11, v217, v10
	v_mul_f32_e32 v10, v216, v10
	v_fma_f32 v6, v216, v9, -v11
	v_fmac_f32_e32 v10, v217, v9
	v_mul_f32_e32 v6, v3, v6
	v_mul_f32_e32 v7, v3, v10
	v_cvt_pk_bf16_f32 v6, v6, s0
	v_cvt_pk_bf16_f32 v7, v7, s0
	ds_write_b16 v12, v6
	ds_write_b16 v12, v7 offset:128
	v_add_u32_e32 v20, 0x8000, v20
	global_load_dwordx2 v[216:217], v20, s[2:3]
	v_add_u32_e32 v12, s10, v12
	v_add_u32_e32 v26, s10, v12
	ds_read_u16 v9, v26
	ds_read_u16 v10, v26 offset:128
	s_waitcnt vmcnt(15) lgkmcnt(4)
	v_lshlrev_b32_e32 v24, 16, v24
	v_lshlrev_b32_e32 v25, 16, v25
	v_mul_f32_e32 v11, v219, v25
	v_mul_f32_e32 v25, v218, v25
	v_fma_f32 v6, v218, v24, -v11
	v_fmac_f32_e32 v25, v219, v24
	v_mul_f32_e32 v6, v3, v6
	v_mul_f32_e32 v7, v3, v25
	v_cvt_pk_bf16_f32 v6, v6, s0
	v_cvt_pk_bf16_f32 v7, v7, s0
	ds_write_b16 v12, v6
	ds_write_b16 v12, v7 offset:128
	global_load_dwordx2 v[218:219], v20, s[2:3] offset:2048
	v_add_u32_e32 v12, s10, v12
	v_add_u32_e32 v26, s10, v12
	ds_read_u16 v24, v26
	ds_read_u16 v25, v26 offset:128
	s_waitcnt vmcnt(15) lgkmcnt(4)
	v_lshlrev_b32_e32 v9, 16, v9
	v_lshlrev_b32_e32 v10, 16, v10
	v_mul_f32_e32 v11, v221, v10
	v_mul_f32_e32 v10, v220, v10
	v_fma_f32 v6, v220, v9, -v11
	v_fmac_f32_e32 v10, v221, v9
	v_mul_f32_e32 v6, v3, v6
	v_mul_f32_e32 v7, v3, v10
	v_cvt_pk_bf16_f32 v6, v6, s0
	v_cvt_pk_bf16_f32 v7, v7, s0
	ds_write_b16 v12, v6
	ds_write_b16 v12, v7 offset:128
	v_add_u32_e32 v21, 0x8000, v21
	global_load_dwordx2 v[220:221], v21, s[2:3]
	v_add_u32_e32 v12, s10, v12
	v_add_u32_e32 v26, s10, v12
	ds_read_u16 v9, v26
	ds_read_u16 v10, v26 offset:128
	s_waitcnt vmcnt(15) lgkmcnt(4)
; DI float bf2f(bf16_t v) { return __uint_as_float(((unsigned)v) << 16); }
; DI bf16_t f2bf(float x) { return (bf16_t)(pack2(x, 0.f) & 0xffffu); }
; DI int tid512() { int t = threadIdx_x_raw(); asm volatile("" : "+v"(t)); return t; }
;   DI void operator()(bf16_t* sCb) const {
;     ...
;       for (int id = tid512(); id < 256 * 128; id += 512) {
;         int row = id >> 7, hf = (id >> 6) & 1, i = id & 63;
;         float2 cs = rope[(size_t)(s0 + row) * 64 + i];
;         bf16_t* q1 = sCb + row * BLD + 128 * hf + i;
;         float x1 = bf2f(q1[0]), x2 = bf2f(q1[64]);
;         q1[0] = f2bf((x1 * cs.x - x2 * cs.y) * sc);
;         q1[64] = f2bf((x1 * cs.y + x2 * cs.x) * sc);
;       }
	v_lshlrev_b32_e32 v24, 16, v24
	v_lshlrev_b32_e32 v25, 16, v25
	v_mul_f32_e32 v11, v223, v25
	v_mul_f32_e32 v25, v222, v25
	v_fma_f32 v6, v222, v24, -v11
	v_fmac_f32_e32 v25, v223, v24
	v_mul_f32_e32 v6, v3, v6
	v_mul_f32_e32 v7, v3, v25
	v_cvt_pk_bf16_f32 v6, v6, s0
	v_cvt_pk_bf16_f32 v7, v7, s0
	ds_write_b16 v12, v6
	ds_write_b16 v12, v7 offset:128
	global_load_dwordx2 v[222:223], v21, s[2:3] offset:2048
	v_add_u32_e32 v12, s10, v12
	v_add_u32_e32 v26, s10, v12
	ds_read_u16 v24, v26
	ds_read_u16 v25, v26 offset:128
	s_waitcnt vmcnt(15) lgkmcnt(4)
	v_lshlrev_b32_e32 v9, 16, v9
	v_lshlrev_b32_e32 v10, 16, v10
	v_mul_f32_e32 v11, v225, v10
	v_mul_f32_e32 v10, v224, v10
	v_fma_f32 v6, v224, v9, -v11
	v_fmac_f32_e32 v10, v225, v9
	v_mul_f32_e32 v6, v3, v6
	v_mul_f32_e32 v7, v3, v10
	v_cvt_pk_bf16_f32 v6, v6, s0
	v_cvt_pk_bf16_f32 v7, v7, s0
	ds_write_b16 v12, v6
	ds_write_b16 v12, v7 offset:128
	v_add_u32_e32 v22, 0x8000, v22
	global_load_dwordx2 v[224:225], v22, s[2:3]
	v_add_u32_e32 v12, s10, v12
	v_add_u32_e32 v26, s10, v12
	ds_read_u16 v9, v26
	ds_read_u16 v10, v26 offset:128
	s_waitcnt vmcnt(15) lgkmcnt(4)
	v_lshlrev_b32_e32 v24, 16, v24
	v_lshlrev_b32_e32 v25, 16, v25
	v_mul_f32_e32 v11, v227, v25
	v_mul_f32_e32 v25, v226, v25
	v_fma_f32 v6, v226, v24, -v11
	v_fmac_f32_e32 v25, v227, v24
	v_mul_f32_e32 v6, v3, v6
	v_mul_f32_e32 v7, v3, v25
	v_cvt_pk_bf16_f32 v6, v6, s0
	v_cvt_pk_bf16_f32 v7, v7, s0
	ds_write_b16 v12, v6
	ds_write_b16 v12, v7 offset:128
	global_load_dwordx2 v[226:227], v22, s[2:3] offset:2048
	v_add_u32_e32 v12, s10, v12
	v_add_u32_e32 v26, s10, v12
	ds_read_u16 v24, v26
	ds_read_u16 v25, v26 offset:128
	s_waitcnt vmcnt(15) lgkmcnt(4)
	v_lshlrev_b32_e32 v9, 16, v9
	v_lshlrev_b32_e32 v10, 16, v10
	v_mul_f32_e32 v11, v229, v10
	v_mul_f32_e32 v10, v228, v10
	v_fma_f32 v6, v228, v9, -v11
	v_fmac_f32_e32 v10, v229, v9
	v_mul_f32_e32 v6, v3, v6
	v_mul_f32_e32 v7, v3, v10
	v_cvt_pk_bf16_f32 v6, v6, s0
	v_cvt_pk_bf16_f32 v7, v7, s0
	ds_write_b16 v12, v6
	ds_write_b16 v12, v7 offset:128
	v_add_u32_e32 v23, 0x8000, v23
	global_load_dwordx2 v[228:229], v23, s[2:3]
	v_add_u32_e32 v12, s10, v12
	v_add_u32_e32 v26, s10, v12
	ds_read_u16 v9, v26
	ds_read_u16 v10, v26 offset:128
	s_waitcnt vmcnt(15) lgkmcnt(4)
	v_lshlrev_b32_e32 v24, 16, v24
	v_lshlrev_b32_e32 v25, 16, v25
	v_mul_f32_e32 v11, v231, v25
	v_mul_f32_e32 v25, v230, v25
	v_fma_f32 v6, v230, v24, -v11
	v_fmac_f32_e32 v25, v231, v24
	v_mul_f32_e32 v6, v3, v6
	v_mul_f32_e32 v7, v3, v25
	v_cvt_pk_bf16_f32 v6, v6, s0
	v_cvt_pk_bf16_f32 v7, v7, s0
	ds_write_b16 v12, v6
	ds_write_b16 v12, v7 offset:128
	global_load_dwordx2 v[230:231], v23, s[2:3] offset:2048
	v_add_u32_e32 v12, s10, v12
	v_add_u32_e32 v26, s10, v12
	ds_read_u16 v24, v26
	ds_read_u16 v25, v26 offset:128
	s_waitcnt vmcnt(15) lgkmcnt(4)
	v_lshlrev_b32_e32 v9, 16, v9
	v_lshlrev_b32_e32 v10, 16, v10
	v_mul_f32_e32 v11, v201, v10
	v_mul_f32_e32 v10, v200, v10
	v_fma_f32 v6, v200, v9, -v11
	v_fmac_f32_e32 v10, v201, v9
	v_mul_f32_e32 v6, v3, v6
	v_mul_f32_e32 v7, v3, v10
	v_cvt_pk_bf16_f32 v6, v6, s0
	v_cvt_pk_bf16_f32 v7, v7, s0
	ds_write_b16 v12, v6
	ds_write_b16 v12, v7 offset:128
	v_add_u32_e32 v16, 0x8000, v16
	global_load_dwordx2 v[200:201], v16, s[2:3]
	v_add_u32_e32 v12, s10, v12
	v_add_u32_e32 v26, s10, v12
	ds_read_u16 v9, v26
	ds_read_u16 v10, v26 offset:128
	s_waitcnt vmcnt(15) lgkmcnt(4)
	v_lshlrev_b32_e32 v24, 16, v24
	v_lshlrev_b32_e32 v25, 16, v25
	v_mul_f32_e32 v11, v203, v25
	v_mul_f32_e32 v25, v202, v25
	v_fma_f32 v6, v202, v24, -v11
	v_fmac_f32_e32 v25, v203, v24
	v_mul_f32_e32 v6, v3, v6
	v_mul_f32_e32 v7, v3, v25
	v_cvt_pk_bf16_f32 v6, v6, s0
	v_cvt_pk_bf16_f32 v7, v7, s0
	ds_write_b16 v12, v6
	ds_write_b16 v12, v7 offset:128
	global_load_dwordx2 v[202:203], v16, s[2:3] offset:2048
	v_add_u32_e32 v12, s10, v12
	v_add_u32_e32 v26, s10, v12
	ds_read_u16 v24, v26
	ds_read_u16 v25, v26 offset:128
	s_waitcnt vmcnt(15) lgkmcnt(4)
	v_lshlrev_b32_e32 v9, 16, v9
	v_lshlrev_b32_e32 v10, 16, v10
	v_mul_f32_e32 v11, v205, v10
	v_mul_f32_e32 v10, v204, v10
	v_fma_f32 v6, v204, v9, -v11
	v_fmac_f32_e32 v10, v205, v9
	v_mul_f32_e32 v6, v3, v6
	v_mul_f32_e32 v7, v3, v10
	v_cvt_pk_bf16_f32 v6, v6, s0
	v_cvt_pk_bf16_f32 v7, v7, s0
	ds_write_b16 v12, v6
	ds_write_b16 v12, v7 offset:128
	v_add_u32_e32 v17, 0x8000, v17
	global_load_dwordx2 v[204:205], v17, s[2:3]
	v_add_u32_e32 v12, s10, v12
	v_add_u32_e32 v26, s10, v12
	ds_read_u16 v9, v26
	ds_read_u16 v10, v26 offset:128
	s_waitcnt vmcnt(15) lgkmcnt(4)
	v_lshlrev_b32_e32 v24, 16, v24
	v_lshlrev_b32_e32 v25, 16, v25
	v_mul_f32_e32 v11, v207, v25
	v_mul_f32_e32 v25, v206, v25
	v_fma_f32 v6, v206, v24, -v11
	v_fmac_f32_e32 v25, v207, v24
	v_mul_f32_e32 v6, v3, v6
	v_mul_f32_e32 v7, v3, v25
	v_cvt_pk_bf16_f32 v6, v6, s0
	v_cvt_pk_bf16_f32 v7, v7, s0
	ds_write_b16 v12, v6
	ds_write_b16 v12, v7 offset:128
	global_load_dwordx2 v[206:207], v17, s[2:3] offset:2048
	v_add_u32_e32 v12, s10, v12
	v_add_u32_e32 v26, s10, v12
	ds_read_u16 v24, v26
	ds_read_u16 v25, v26 offset:128
	s_waitcnt vmcnt(15) lgkmcnt(4)
	v_lshlrev_b32_e32 v9, 16, v9
	v_lshlrev_b32_e32 v10, 16, v10
	v_mul_f32_e32 v11, v209, v10
	v_mul_f32_e32 v10, v208, v10
	v_fma_f32 v6, v208, v9, -v11
	v_fmac_f32_e32 v10, v209, v9
	v_mul_f32_e32 v6, v3, v6
	v_mul_f32_e32 v7, v3, v10
	v_cvt_pk_bf16_f32 v6, v6, s0
	v_cvt_pk_bf16_f32 v7, v7, s0
	ds_write_b16 v12, v6
	ds_write_b16 v12, v7 offset:128
	v_add_u32_e32 v18, 0x8000, v18
	global_load_dwordx2 v[208:209], v18, s[2:3]
	v_add_u32_e32 v12, s10, v12
	v_add_u32_e32 v26, s10, v12
	ds_read_u16 v9, v26
	ds_read_u16 v10, v26 offset:128
	s_waitcnt vmcnt(15) lgkmcnt(4)
; DI float bf2f(bf16_t v) { return __uint_as_float(((unsigned)v) << 16); }
; DI bf16_t f2bf(float x) { return (bf16_t)(pack2(x, 0.f) & 0xffffu); }
; DI int tid512() { int t = threadIdx_x_raw(); asm volatile("" : "+v"(t)); return t; }
;   DI void operator()(bf16_t* sCb) const {
;     ...
;       for (int id = tid512(); id < 256 * 128; id += 512) {
;         int row = id >> 7, hf = (id >> 6) & 1, i = id & 63;
;         float2 cs = rope[(size_t)(s0 + row) * 64 + i];
;         bf16_t* q1 = sCb + row * BLD + 128 * hf + i;
;         float x1 = bf2f(q1[0]), x2 = bf2f(q1[64]);
;         q1[0] = f2bf((x1 * cs.x - x2 * cs.y) * sc);
;         q1[64] = f2bf((x1 * cs.y + x2 * cs.x) * sc);
;       }
	v_lshlrev_b32_e32 v24, 16, v24
	v_lshlrev_b32_e32 v25, 16, v25
	v_mul_f32_e32 v11, v211, v25
	v_mul_f32_e32 v25, v210, v25
	v_fma_f32 v6, v210, v24, -v11
	v_fmac_f32_e32 v25, v211, v24
	v_mul_f32_e32 v6, v3, v6
	v_mul_f32_e32 v7, v3, v25
	v_cvt_pk_bf16_f32 v6, v6, s0
	v_cvt_pk_bf16_f32 v7, v7, s0
	ds_write_b16 v12, v6
	ds_write_b16 v12, v7 offset:128
	global_load_dwordx2 v[210:211], v18, s[2:3] offset:2048
	v_add_u32_e32 v12, s10, v12
	v_add_u32_e32 v26, s10, v12
	ds_read_u16 v24, v26
	ds_read_u16 v25, v26 offset:128
	s_waitcnt vmcnt(15) lgkmcnt(4)
	v_lshlrev_b32_e32 v9, 16, v9
	v_lshlrev_b32_e32 v10, 16, v10
	v_mul_f32_e32 v11, v213, v10
	v_mul_f32_e32 v10, v212, v10
	v_fma_f32 v6, v212, v9, -v11
	v_fmac_f32_e32 v10, v213, v9
	v_mul_f32_e32 v6, v3, v6
	v_mul_f32_e32 v7, v3, v10
	v_cvt_pk_bf16_f32 v6, v6, s0
	v_cvt_pk_bf16_f32 v7, v7, s0
	ds_write_b16 v12, v6
	ds_write_b16 v12, v7 offset:128
	v_add_u32_e32 v19, 0x8000, v19
	global_load_dwordx2 v[212:213], v19, s[2:3]
	v_add_u32_e32 v12, s10, v12
	v_add_u32_e32 v26, s10, v12
	ds_read_u16 v9, v26
	ds_read_u16 v10, v26 offset:128
	s_waitcnt vmcnt(15) lgkmcnt(4)
	v_lshlrev_b32_e32 v24, 16, v24
	v_lshlrev_b32_e32 v25, 16, v25
	v_mul_f32_e32 v11, v215, v25
	v_mul_f32_e32 v25, v214, v25
	v_fma_f32 v6, v214, v24, -v11
	v_fmac_f32_e32 v25, v215, v24
	v_mul_f32_e32 v6, v3, v6
	v_mul_f32_e32 v7, v3, v25
	v_cvt_pk_bf16_f32 v6, v6, s0
	v_cvt_pk_bf16_f32 v7, v7, s0
	ds_write_b16 v12, v6
	ds_write_b16 v12, v7 offset:128
	global_load_dwordx2 v[214:215], v19, s[2:3] offset:2048
	v_add_u32_e32 v12, s10, v12
	v_add_u32_e32 v26, s10, v12
	ds_read_u16 v24, v26
	ds_read_u16 v25, v26 offset:128
	s_waitcnt vmcnt(15) lgkmcnt(4)
	v_lshlrev_b32_e32 v9, 16, v9
	v_lshlrev_b32_e32 v10, 16, v10
	v_mul_f32_e32 v11, v217, v10
	v_mul_f32_e32 v10, v216, v10
	v_fma_f32 v6, v216, v9, -v11
	v_fmac_f32_e32 v10, v217, v9
	v_mul_f32_e32 v6, v3, v6
	v_mul_f32_e32 v7, v3, v10
	v_cvt_pk_bf16_f32 v6, v6, s0
	v_cvt_pk_bf16_f32 v7, v7, s0
	ds_write_b16 v12, v6
	ds_write_b16 v12, v7 offset:128
	v_add_u32_e32 v20, 0x8000, v20
	global_load_dwordx2 v[216:217], v20, s[2:3]
	v_add_u32_e32 v12, s10, v12
	v_add_u32_e32 v26, s10, v12
	ds_read_u16 v9, v26
	ds_read_u16 v10, v26 offset:128
	s_waitcnt vmcnt(15) lgkmcnt(4)
	v_lshlrev_b32_e32 v24, 16, v24
	v_lshlrev_b32_e32 v25, 16, v25
	v_mul_f32_e32 v11, v219, v25
	v_mul_f32_e32 v25, v218, v25
	v_fma_f32 v6, v218, v24, -v11
	v_fmac_f32_e32 v25, v219, v24
	v_mul_f32_e32 v6, v3, v6
	v_mul_f32_e32 v7, v3, v25
	v_cvt_pk_bf16_f32 v6, v6, s0
	v_cvt_pk_bf16_f32 v7, v7, s0
	ds_write_b16 v12, v6
	ds_write_b16 v12, v7 offset:128
	global_load_dwordx2 v[218:219], v20, s[2:3] offset:2048
	v_add_u32_e32 v12, s10, v12
	v_add_u32_e32 v26, s10, v12
	ds_read_u16 v24, v26
	ds_read_u16 v25, v26 offset:128
	s_waitcnt vmcnt(15) lgkmcnt(4)
	v_lshlrev_b32_e32 v9, 16, v9
	v_lshlrev_b32_e32 v10, 16, v10
	v_mul_f32_e32 v11, v221, v10
	v_mul_f32_e32 v10, v220, v10
	v_fma_f32 v6, v220, v9, -v11
	v_fmac_f32_e32 v10, v221, v9
	v_mul_f32_e32 v6, v3, v6
	v_mul_f32_e32 v7, v3, v10
	v_cvt_pk_bf16_f32 v6, v6, s0
	v_cvt_pk_bf16_f32 v7, v7, s0
	ds_write_b16 v12, v6
	ds_write_b16 v12, v7 offset:128
	v_add_u32_e32 v21, 0x8000, v21
	global_load_dwordx2 v[220:221], v21, s[2:3]
	v_add_u32_e32 v12, s10, v12
	v_add_u32_e32 v26, s10, v12
	ds_read_u16 v9, v26
	ds_read_u16 v10, v26 offset:128
	s_waitcnt vmcnt(15) lgkmcnt(4)
	v_lshlrev_b32_e32 v24, 16, v24
	v_lshlrev_b32_e32 v25, 16, v25
	v_mul_f32_e32 v11, v223, v25
	v_mul_f32_e32 v25, v222, v25
	v_fma_f32 v6, v222, v24, -v11
	v_fmac_f32_e32 v25, v223, v24
	v_mul_f32_e32 v6, v3, v6
	v_mul_f32_e32 v7, v3, v25
	v_cvt_pk_bf16_f32 v6, v6, s0
	v_cvt_pk_bf16_f32 v7, v7, s0
	ds_write_b16 v12, v6
	ds_write_b16 v12, v7 offset:128
	global_load_dwordx2 v[222:223], v21, s[2:3] offset:2048
	v_add_u32_e32 v12, s10, v12
	v_add_u32_e32 v26, s10, v12
	ds_read_u16 v24, v26
	ds_read_u16 v25, v26 offset:128
	s_waitcnt vmcnt(15) lgkmcnt(4)
	v_lshlrev_b32_e32 v9, 16, v9
	v_lshlrev_b32_e32 v10, 16, v10
	v_mul_f32_e32 v11, v225, v10
	v_mul_f32_e32 v10, v224, v10
	v_fma_f32 v6, v224, v9, -v11
	v_fmac_f32_e32 v10, v225, v9
	v_mul_f32_e32 v6, v3, v6
	v_mul_f32_e32 v7, v3, v10
	v_cvt_pk_bf16_f32 v6, v6, s0
	v_cvt_pk_bf16_f32 v7, v7, s0
	ds_write_b16 v12, v6
	ds_write_b16 v12, v7 offset:128
	v_add_u32_e32 v22, 0x8000, v22
	global_load_dwordx2 v[224:225], v22, s[2:3]
	v_add_u32_e32 v12, s10, v12
	v_add_u32_e32 v26, s10, v12
	ds_read_u16 v9, v26
	ds_read_u16 v10, v26 offset:128
	s_waitcnt vmcnt(15) lgkmcnt(4)
	v_lshlrev_b32_e32 v24, 16, v24
	v_lshlrev_b32_e32 v25, 16, v25
	v_mul_f32_e32 v11, v227, v25
	v_mul_f32_e32 v25, v226, v25
	v_fma_f32 v6, v226, v24, -v11
	v_fmac_f32_e32 v25, v227, v24
	v_mul_f32_e32 v6, v3, v6
	v_mul_f32_e32 v7, v3, v25
	v_cvt_pk_bf16_f32 v6, v6, s0
	v_cvt_pk_bf16_f32 v7, v7, s0
	ds_write_b16 v12, v6
	ds_write_b16 v12, v7 offset:128
	global_load_dwordx2 v[226:227], v22, s[2:3] offset:2048
	v_add_u32_e32 v12, s10, v12
	v_add_u32_e32 v26, s10, v12
	ds_read_u16 v24, v26
	ds_read_u16 v25, v26 offset:128
	s_waitcnt vmcnt(15) lgkmcnt(4)
	v_lshlrev_b32_e32 v9, 16, v9
	v_lshlrev_b32_e32 v10, 16, v10
	v_mul_f32_e32 v11, v229, v10
	v_mul_f32_e32 v10, v228, v10
	v_fma_f32 v6, v228, v9, -v11
	v_fmac_f32_e32 v10, v229, v9
	v_mul_f32_e32 v6, v3, v6
	v_mul_f32_e32 v7, v3, v10
	v_cvt_pk_bf16_f32 v6, v6, s0
	v_cvt_pk_bf16_f32 v7, v7, s0
	ds_write_b16 v12, v6
	ds_write_b16 v12, v7 offset:128
	v_add_u32_e32 v23, 0x8000, v23
	global_load_dwordx2 v[228:229], v23, s[2:3]
	v_add_u32_e32 v12, s10, v12
	v_add_u32_e32 v26, s10, v12
	ds_read_u16 v9, v26
	ds_read_u16 v10, v26 offset:128
	s_waitcnt vmcnt(15) lgkmcnt(4)
; DI float bf2f(bf16_t v) { return __uint_as_float(((unsigned)v) << 16); }
; DI bf16_t f2bf(float x) { return (bf16_t)(pack2(x, 0.f) & 0xffffu); }
; DI int tid512() { int t = threadIdx_x_raw(); asm volatile("" : "+v"(t)); return t; }
;   DI void operator()(bf16_t* sCb) const {
;     ...
;       for (int id = tid512(); id < 256 * 128; id += 512) {
;         int row = id >> 7, hf = (id >> 6) & 1, i = id & 63;
;         float2 cs = rope[(size_t)(s0 + row) * 64 + i];
;         bf16_t* q1 = sCb + row * BLD + 128 * hf + i;
;         float x1 = bf2f(q1[0]), x2 = bf2f(q1[64]);
;         q1[0] = f2bf((x1 * cs.x - x2 * cs.y) * sc);
;         q1[64] = f2bf((x1 * cs.y + x2 * cs.x) * sc);
;       }
	v_lshlrev_b32_e32 v24, 16, v24
	v_lshlrev_b32_e32 v25, 16, v25
	v_mul_f32_e32 v11, v231, v25
	v_mul_f32_e32 v25, v230, v25
	v_fma_f32 v6, v230, v24, -v11
	v_fmac_f32_e32 v25, v231, v24
	v_mul_f32_e32 v6, v3, v6
	v_mul_f32_e32 v7, v3, v25
	v_cvt_pk_bf16_f32 v6, v6, s0
	v_cvt_pk_bf16_f32 v7, v7, s0
	ds_write_b16 v12, v6
	ds_write_b16 v12, v7 offset:128
	global_load_dwordx2 v[230:231], v23, s[2:3] offset:2048
	v_add_u32_e32 v12, s10, v12
	v_add_u32_e32 v26, s10, v12
	ds_read_u16 v24, v26
	ds_read_u16 v25, v26 offset:128
	s_waitcnt vmcnt(15) lgkmcnt(4)
	v_lshlrev_b32_e32 v9, 16, v9
	v_lshlrev_b32_e32 v10, 16, v10
	v_mul_f32_e32 v11, v201, v10
	v_mul_f32_e32 v10, v200, v10
	v_fma_f32 v6, v200, v9, -v11
	v_fmac_f32_e32 v10, v201, v9
	v_mul_f32_e32 v6, v3, v6
	v_mul_f32_e32 v7, v3, v10
	v_cvt_pk_bf16_f32 v6, v6, s0
	v_cvt_pk_bf16_f32 v7, v7, s0
	ds_write_b16 v12, v6
	ds_write_b16 v12, v7 offset:128
	v_add_u32_e32 v12, s10, v12
	v_add_u32_e32 v26, s10, v12
	ds_read_u16 v9, v26
	ds_read_u16 v10, v26 offset:128
	s_waitcnt vmcnt(14) lgkmcnt(4)
	v_lshlrev_b32_e32 v24, 16, v24
	v_lshlrev_b32_e32 v25, 16, v25
	v_mul_f32_e32 v11, v203, v25
	v_mul_f32_e32 v25, v202, v25
	v_fma_f32 v6, v202, v24, -v11
	v_fmac_f32_e32 v25, v203, v24
	v_mul_f32_e32 v6, v3, v6
	v_mul_f32_e32 v7, v3, v25
	v_cvt_pk_bf16_f32 v6, v6, s0
	v_cvt_pk_bf16_f32 v7, v7, s0
	ds_write_b16 v12, v6
	ds_write_b16 v12, v7 offset:128
	v_add_u32_e32 v12, s10, v12
	v_add_u32_e32 v26, s10, v12
	ds_read_u16 v24, v26
	ds_read_u16 v25, v26 offset:128
	s_waitcnt vmcnt(13) lgkmcnt(4)
	v_lshlrev_b32_e32 v9, 16, v9
	v_lshlrev_b32_e32 v10, 16, v10
	v_mul_f32_e32 v11, v205, v10
	v_mul_f32_e32 v10, v204, v10
	v_fma_f32 v6, v204, v9, -v11
	v_fmac_f32_e32 v10, v205, v9
	v_mul_f32_e32 v6, v3, v6
	v_mul_f32_e32 v7, v3, v10
	v_cvt_pk_bf16_f32 v6, v6, s0
	v_cvt_pk_bf16_f32 v7, v7, s0
	ds_write_b16 v12, v6
	ds_write_b16 v12, v7 offset:128
	v_add_u32_e32 v12, s10, v12
	v_add_u32_e32 v26, s10, v12
	ds_read_u16 v9, v26
	ds_read_u16 v10, v26 offset:128
	s_waitcnt vmcnt(12) lgkmcnt(4)
	v_lshlrev_b32_e32 v24, 16, v24
	v_lshlrev_b32_e32 v25, 16, v25
	v_mul_f32_e32 v11, v207, v25
	v_mul_f32_e32 v25, v206, v25
	v_fma_f32 v6, v206, v24, -v11
	v_fmac_f32_e32 v25, v207, v24
	v_mul_f32_e32 v6, v3, v6
	v_mul_f32_e32 v7, v3, v25
	v_cvt_pk_bf16_f32 v6, v6, s0
	v_cvt_pk_bf16_f32 v7, v7, s0
	ds_write_b16 v12, v6
	ds_write_b16 v12, v7 offset:128
	v_add_u32_e32 v12, s10, v12
	v_add_u32_e32 v26, s10, v12
	ds_read_u16 v24, v26
	ds_read_u16 v25, v26 offset:128
	s_waitcnt vmcnt(11) lgkmcnt(4)
	v_lshlrev_b32_e32 v9, 16, v9
	v_lshlrev_b32_e32 v10, 16, v10
	v_mul_f32_e32 v11, v209, v10
	v_mul_f32_e32 v10, v208, v10
	v_fma_f32 v6, v208, v9, -v11
	v_fmac_f32_e32 v10, v209, v9
	v_mul_f32_e32 v6, v3, v6
	v_mul_f32_e32 v7, v3, v10
	v_cvt_pk_bf16_f32 v6, v6, s0
	v_cvt_pk_bf16_f32 v7, v7, s0
	ds_write_b16 v12, v6
	ds_write_b16 v12, v7 offset:128
	v_add_u32_e32 v12, s10, v12
	v_add_u32_e32 v26, s10, v12
	ds_read_u16 v9, v26
	ds_read_u16 v10, v26 offset:128
	s_waitcnt vmcnt(10) lgkmcnt(4)
	v_lshlrev_b32_e32 v24, 16, v24
	v_lshlrev_b32_e32 v25, 16, v25
	v_mul_f32_e32 v11, v211, v25
	v_mul_f32_e32 v25, v210, v25
	v_fma_f32 v6, v210, v24, -v11
	v_fmac_f32_e32 v25, v211, v24
	v_mul_f32_e32 v6, v3, v6
	v_mul_f32_e32 v7, v3, v25
	v_cvt_pk_bf16_f32 v6, v6, s0
	v_cvt_pk_bf16_f32 v7, v7, s0
	ds_write_b16 v12, v6
	ds_write_b16 v12, v7 offset:128
	v_add_u32_e32 v12, s10, v12
	v_add_u32_e32 v26, s10, v12
	ds_read_u16 v24, v26
	ds_read_u16 v25, v26 offset:128
	s_waitcnt vmcnt(9) lgkmcnt(4)
	v_lshlrev_b32_e32 v9, 16, v9
	v_lshlrev_b32_e32 v10, 16, v10
	v_mul_f32_e32 v11, v213, v10
	v_mul_f32_e32 v10, v212, v10
	v_fma_f32 v6, v212, v9, -v11
	v_fmac_f32_e32 v10, v213, v9
	v_mul_f32_e32 v6, v3, v6
	v_mul_f32_e32 v7, v3, v10
	v_cvt_pk_bf16_f32 v6, v6, s0
	v_cvt_pk_bf16_f32 v7, v7, s0
	ds_write_b16 v12, v6
	ds_write_b16 v12, v7 offset:128
	v_add_u32_e32 v12, s10, v12
	v_add_u32_e32 v26, s10, v12
	ds_read_u16 v9, v26
	ds_read_u16 v10, v26 offset:128
	s_waitcnt vmcnt(8) lgkmcnt(4)
; DI float bf2f(bf16_t v) { return __uint_as_float(((unsigned)v) << 16); }
; DI bf16_t f2bf(float x) { return (bf16_t)(pack2(x, 0.f) & 0xffffu); }
; DI int tid512() { int t = threadIdx_x_raw(); asm volatile("" : "+v"(t)); return t; }
;   DI void operator()(bf16_t* sCb) const {
;     ...
;       for (int id = tid512(); id < 256 * 128; id += 512) {
;         int row = id >> 7, hf = (id >> 6) & 1, i = id & 63;
;         float2 cs = rope[(size_t)(s0 + row) * 64 + i];
;         bf16_t* q1 = sCb + row * BLD + 128 * hf + i;
;         float x1 = bf2f(q1[0]), x2 = bf2f(q1[64]);
;         q1[0] = f2bf((x1 * cs.x - x2 * cs.y) * sc);
;         q1[64] = f2bf((x1 * cs.y + x2 * cs.x) * sc);
;       }
	v_lshlrev_b32_e32 v24, 16, v24
	v_lshlrev_b32_e32 v25, 16, v25
	v_mul_f32_e32 v11, v215, v25
	v_mul_f32_e32 v25, v214, v25
	v_fma_f32 v6, v214, v24, -v11
	v_fmac_f32_e32 v25, v215, v24
	v_mul_f32_e32 v6, v3, v6
	v_mul_f32_e32 v7, v3, v25
	v_cvt_pk_bf16_f32 v6, v6, s0
	v_cvt_pk_bf16_f32 v7, v7, s0
	ds_write_b16 v12, v6
	ds_write_b16 v12, v7 offset:128
	v_add_u32_e32 v12, s10, v12
	v_add_u32_e32 v26, s10, v12
	ds_read_u16 v24, v26
	ds_read_u16 v25, v26 offset:128
	s_waitcnt vmcnt(7) lgkmcnt(4)
	v_lshlrev_b32_e32 v9, 16, v9
	v_lshlrev_b32_e32 v10, 16, v10
	v_mul_f32_e32 v11, v217, v10
	v_mul_f32_e32 v10, v216, v10
	v_fma_f32 v6, v216, v9, -v11
	v_fmac_f32_e32 v10, v217, v9
	v_mul_f32_e32 v6, v3, v6
	v_mul_f32_e32 v7, v3, v10
	v_cvt_pk_bf16_f32 v6, v6, s0
	v_cvt_pk_bf16_f32 v7, v7, s0
	ds_write_b16 v12, v6
	ds_write_b16 v12, v7 offset:128
	v_add_u32_e32 v12, s10, v12
	v_add_u32_e32 v26, s10, v12
	ds_read_u16 v9, v26
	ds_read_u16 v10, v26 offset:128
	s_waitcnt vmcnt(6) lgkmcnt(4)
	v_lshlrev_b32_e32 v24, 16, v24
	v_lshlrev_b32_e32 v25, 16, v25
	v_mul_f32_e32 v11, v219, v25
	v_mul_f32_e32 v25, v218, v25
	v_fma_f32 v6, v218, v24, -v11
	v_fmac_f32_e32 v25, v219, v24
	v_mul_f32_e32 v6, v3, v6
	v_mul_f32_e32 v7, v3, v25
	v_cvt_pk_bf16_f32 v6, v6, s0
	v_cvt_pk_bf16_f32 v7, v7, s0
	ds_write_b16 v12, v6
	ds_write_b16 v12, v7 offset:128
	v_add_u32_e32 v12, s10, v12
	v_add_u32_e32 v26, s10, v12
	ds_read_u16 v24, v26
	ds_read_u16 v25, v26 offset:128
	s_waitcnt vmcnt(5) lgkmcnt(4)
	v_lshlrev_b32_e32 v9, 16, v9
	v_lshlrev_b32_e32 v10, 16, v10
	v_mul_f32_e32 v11, v221, v10
	v_mul_f32_e32 v10, v220, v10
	v_fma_f32 v6, v220, v9, -v11
	v_fmac_f32_e32 v10, v221, v9
	v_mul_f32_e32 v6, v3, v6
	v_mul_f32_e32 v7, v3, v10
	v_cvt_pk_bf16_f32 v6, v6, s0
	v_cvt_pk_bf16_f32 v7, v7, s0
	ds_write_b16 v12, v6
	ds_write_b16 v12, v7 offset:128
	v_add_u32_e32 v12, s10, v12
	v_add_u32_e32 v26, s10, v12
	ds_read_u16 v9, v26
	ds_read_u16 v10, v26 offset:128
	s_waitcnt vmcnt(4) lgkmcnt(4)
	v_lshlrev_b32_e32 v24, 16, v24
	v_lshlrev_b32_e32 v25, 16, v25
	v_mul_f32_e32 v11, v223, v25
	v_mul_f32_e32 v25, v222, v25
	v_fma_f32 v6, v222, v24, -v11
	v_fmac_f32_e32 v25, v223, v24
	v_mul_f32_e32 v6, v3, v6
	v_mul_f32_e32 v7, v3, v25
	v_cvt_pk_bf16_f32 v6, v6, s0
	v_cvt_pk_bf16_f32 v7, v7, s0
	ds_write_b16 v12, v6
	ds_write_b16 v12, v7 offset:128
	v_add_u32_e32 v12, s10, v12
	v_add_u32_e32 v26, s10, v12
	ds_read_u16 v24, v26
	ds_read_u16 v25, v26 offset:128
	s_waitcnt vmcnt(3) lgkmcnt(4)
	v_lshlrev_b32_e32 v9, 16, v9
	v_lshlrev_b32_e32 v10, 16, v10
	v_mul_f32_e32 v11, v225, v10
	v_mul_f32_e32 v10, v224, v10
	v_fma_f32 v6, v224, v9, -v11
	v_fmac_f32_e32 v10, v225, v9
	v_mul_f32_e32 v6, v3, v6
	v_mul_f32_e32 v7, v3, v10
	v_cvt_pk_bf16_f32 v6, v6, s0
	v_cvt_pk_bf16_f32 v7, v7, s0
	ds_write_b16 v12, v6
	ds_write_b16 v12, v7 offset:128
	v_add_u32_e32 v12, s10, v12
	v_add_u32_e32 v26, s10, v12
	ds_read_u16 v9, v26
	ds_read_u16 v10, v26 offset:128
	s_waitcnt vmcnt(2) lgkmcnt(4)
	v_lshlrev_b32_e32 v24, 16, v24
	v_lshlrev_b32_e32 v25, 16, v25
	v_mul_f32_e32 v11, v227, v25
	v_mul_f32_e32 v25, v226, v25
	v_fma_f32 v6, v226, v24, -v11
	v_fmac_f32_e32 v25, v227, v24
	v_mul_f32_e32 v6, v3, v6
	v_mul_f32_e32 v7, v3, v25
	v_cvt_pk_bf16_f32 v6, v6, s0
	v_cvt_pk_bf16_f32 v7, v7, s0
	ds_write_b16 v12, v6
	ds_write_b16 v12, v7 offset:128
	v_add_u32_e32 v12, s10, v12
	v_add_u32_e32 v26, s10, v12
	ds_read_u16 v24, v26
	ds_read_u16 v25, v26 offset:128
	s_waitcnt vmcnt(1) lgkmcnt(4)
	v_lshlrev_b32_e32 v9, 16, v9
	v_lshlrev_b32_e32 v10, 16, v10
	v_mul_f32_e32 v11, v229, v10
	v_mul_f32_e32 v10, v228, v10
	v_fma_f32 v6, v228, v9, -v11
	v_fmac_f32_e32 v10, v229, v9
	v_mul_f32_e32 v6, v3, v6
	v_mul_f32_e32 v7, v3, v10
	v_cvt_pk_bf16_f32 v6, v6, s0
	v_cvt_pk_bf16_f32 v7, v7, s0
	ds_write_b16 v12, v6
	ds_write_b16 v12, v7 offset:128
	v_add_u32_e32 v12, s10, v12
	s_waitcnt vmcnt(0) lgkmcnt(2)
	v_lshlrev_b32_e32 v24, 16, v24
	v_lshlrev_b32_e32 v25, 16, v25
	v_mul_f32_e32 v11, v231, v25
	v_mul_f32_e32 v25, v230, v25
	v_fma_f32 v6, v230, v24, -v11
	v_fmac_f32_e32 v25, v231, v24
	v_mul_f32_e32 v6, v3, v6
	v_mul_f32_e32 v7, v3, v25
	v_cvt_pk_bf16_f32 v6, v6, s0
	v_cvt_pk_bf16_f32 v7, v7, s0
	ds_write_b16 v12, v6
	ds_write_b16 v12, v7 offset:128
	v_add_u32_e32 v12, s10, v12
